# A11: A8 + less LDS traffic in the RWKV scan phase (other row's v read as b32; helper exchange reads / group-product rewrite only in the lanes that need them)
# speedup vs baseline: 1.0033x; 1.0033x over previous
.LBB0_185:
	s_and_b32 s17, s16, 1
	s_and_saveexec_b64 s[0:1], s[36:37]
	s_xor_b64 s[8:9], exec, s[0:1]
	s_cbranch_execz .LBB0_203
	s_ashr_i32 s2, s16, 5
	v_readlane_b32 s0, v251, 28
	s_ashr_i32 s3, s2, 31
	s_bfe_u32 s12, s16, 0x40001
	v_readlane_b32 s1, v251, 29
	s_lshl_b64 s[10:11], s[2:3], 11
	s_mov_b32 s15, s1
	s_lshl_b32 s14, s12, 7
	s_lshl_b32 s18, s12, 6
	v_lshl_add_u64 v[16:17], s[10:11], 0, v[104:105]
	v_lshl_add_u64 v[34:35], v[106:107], 0, s[14:15]
	s_movk_i32 s13, 0x1800
	v_lshl_add_u64 v[36:37], v[108:109], 0, s[14:15]
	v_or_b32_e32 v2, s18, v1
	v_readlane_b32 s40, v251, 9
	v_mad_u64_u32 v[14:15], s[0:1], v16, s13, v[34:35]
	v_mad_u64_u32 v[18:19], s[0:1], v16, s13, v[36:37]
	v_lshlrev_b32_e32 v12, 2, v2
	v_readlane_b32 s44, v251, 13
	v_readlane_b32 s45, v251, 14
	v_mad_i32_i24 v15, v17, s13, v15
	v_mad_i32_i24 v19, v17, s13, v19
	v_readlane_b32 s42, v251, 11
	v_readlane_b32 s43, v251, 12
	v_add_co_u32_e32 v10, vcc, s73, v14
	global_load_dwordx4 v[2:5], v12, s[44:45]
	global_load_dwordx2 v[20:21], v[14:15], off
	global_load_dwordx2 v[22:23], v[14:15], off offset:2048
	global_load_dwordx2 v[30:31], v[18:19], off
	global_load_dwordx4 v[6:9], v12, s[42:43]
	global_load_dwordx2 v[32:33], v[18:19], off offset:2048
	v_addc_co_u32_e32 v11, vcc, 0, v15, vcc
	v_readlane_b32 s46, v251, 15
	v_readlane_b32 s47, v251, 16
	global_load_dwordx2 v[24:25], v[10:11], off
	s_nop 3
	global_load_dwordx4 v[10:13], v12, s[46:47]
	s_waitcnt vmcnt(9)
	v_or_b32_e32 v26, s17, v1
	v_cmp_eq_u32_e64 s[0:1], 0, v26
	s_lshl_b32 s19, s12, 2
	v_readlane_b32 s12, v248, 15
	v_readlane_b32 s13, v248, 16
	s_add_u32 s12, s12, s19
	s_addc_u32 s13, s13, 0
	v_lshlrev_b64 v[16:17], 6, v[16:17]
	s_mov_b64 s[24:25], s[14:15]
	v_readlane_b32 s41, v251, 10
	v_readlane_b32 s48, v251, 17
	v_readlane_b32 s49, v251, 18
	v_readlane_b32 s50, v251, 19
	v_readlane_b32 s51, v251, 20
	v_readlane_b32 s52, v251, 21
	v_readlane_b32 s53, v251, 22
	v_readlane_b32 s54, v251, 23
	v_readlane_b32 s55, v251, 24
	s_waitcnt vmcnt(7)
	v_pk_add_f32 v[38:39], v[2:3], 1.0 op_sel_hi:[1,0] neg_lo:[1,0] neg_hi:[1,0]
	s_waitcnt vmcnt(5)
	v_lshlrev_b32_e32 v28, 16, v22
	v_and_b32_e32 v29, 0xffff0000, v22
	s_waitcnt vmcnt(2)
	v_lshlrev_b32_e32 v50, 16, v32
	v_and_b32_e32 v51, 0xffff0000, v32
	v_lshlrev_b32_e32 v26, 16, v20
	v_and_b32_e32 v27, 0xffff0000, v20
	v_lshlrev_b32_e32 v54, 16, v21
	v_and_b32_e32 v55, 0xffff0000, v21
	v_lshlrev_b32_e32 v43, 16, v30
	v_and_b32_e32 v45, 0xffff0000, v30
	v_pk_mul_f32 v[20:21], v[6:7], v[28:29]
	s_waitcnt vmcnt(1)
	v_and_b32_e32 v32, 0xffff0000, v25
	v_lshlrev_b32_e32 v30, 16, v25
	v_and_b32_e32 v44, 0xffff0000, v24
	v_lshlrev_b32_e32 v42, 16, v24
	v_pk_fma_f32 v[24:25], v[50:51], v[2:3], v[38:39]
	v_pk_add_f32 v[40:41], v[4:5], 1.0 op_sel_hi:[1,0] neg_lo:[1,0] neg_hi:[1,0]
	v_lshlrev_b32_e32 v56, 16, v33
	v_and_b32_e32 v57, 0xffff0000, v33
	v_pk_mul_f32 v[60:61], v[20:21], v[50:51]
	v_pk_mul_f32 v[50:51], v[24:25], v[28:29]
	v_lshlrev_b32_e32 v52, 16, v23
	v_and_b32_e32 v53, 0xffff0000, v23
	v_lshlrev_b32_e32 v48, 16, v31
	v_and_b32_e32 v31, 0xffff0000, v31
	v_pk_fma_f32 v[58:59], v[56:57], v[4:5], v[40:41]
	v_pk_mul_f32 v[24:25], v[50:51], v[26:27]
	v_pk_mul_f32 v[22:23], v[8:9], v[52:53]
	v_fma_f32 v33, v20, v20, 0
	v_exp_f32_e32 v49, v31
	v_pk_mul_f32 v[52:53], v[58:59], v[52:53]
	v_fma_f32 v31, v60, v26, 0
	v_fma_f32 v64, v50, v26, 0
	s_waitcnt vmcnt(0)
	v_fma_f32 v24, v24, v10, 0
	v_pk_mul_f32 v[56:57], v[22:23], v[56:57]
	v_fmac_f32_e32 v33, v21, v21
	v_pk_mul_f32 v[28:29], v[52:53], v[54:55]
	v_fmac_f32_e32 v31, v61, v27
	v_fmac_f32_e32 v64, v51, v27
	v_fmac_f32_e32 v24, v25, v11
	v_exp_f32_e32 v48, v48
	v_fmac_f32_e32 v33, v22, v22
	v_fmac_f32_e32 v31, v56, v54
	v_fmac_f32_e32 v64, v52, v54
	v_fmac_f32_e32 v24, v28, v12
	v_fmac_f32_e32 v33, v23, v23
	v_fmac_f32_e32 v31, v57, v55
	v_fmac_f32_e32 v64, v53, v55
	v_fmac_f32_e32 v24, v29, v13
	s_nop 1
	v_add_f32_dpp v33, v33, v33 quad_perm:[1,0,3,2] row_mask:0xf bank_mask:0xf
	v_add_f32_dpp v24, v24, v24 quad_perm:[1,0,3,2] row_mask:0xf bank_mask:0xf
	v_add_f32_dpp v31, v31, v31 quad_perm:[1,0,3,2] row_mask:0xf bank_mask:0xf
	v_add_f32_dpp v64, v64, v64 quad_perm:[1,0,3,2] row_mask:0xf bank_mask:0xf
	v_add_f32_dpp v33, v33, v33 quad_perm:[2,3,0,1] row_mask:0xf bank_mask:0xf
	v_add_f32_dpp v24, v24, v24 quad_perm:[2,3,0,1] row_mask:0xf bank_mask:0xf
	v_add_f32_dpp v31, v31, v31 quad_perm:[2,3,0,1] row_mask:0xf bank_mask:0xf
	v_add_f32_dpp v64, v64, v64 quad_perm:[2,3,0,1] row_mask:0xf bank_mask:0xf
	v_add_f32_dpp v33, v33, v33 row_half_mirror row_mask:0xf bank_mask:0xf
	v_add_f32_dpp v24, v24, v24 row_half_mirror row_mask:0xf bank_mask:0xf
	v_add_f32_dpp v31, v31, v31 row_half_mirror row_mask:0xf bank_mask:0xf
	v_add_f32_dpp v64, v64, v64 row_half_mirror row_mask:0xf bank_mask:0xf
	v_add_f32_dpp v33, v33, v33 row_mirror row_mask:0xf bank_mask:0xf
	v_add_f32_dpp v24, v24, v24 row_mirror row_mask:0xf bank_mask:0xf
	v_add_f32_dpp v31, v31, v31 row_mirror row_mask:0xf bank_mask:0xf
	v_add_f32_dpp v64, v64, v64 row_mirror row_mask:0xf bank_mask:0xf
	s_nop 0
	v_exp_f32_e32 v46, v43
	v_max_f32_e32 v25, v33, v33
	v_max_f32_e32 v25, 0x179abe15, v25
	v_exp_f32_e32 v47, v45
	v_pk_mul_f32 v[62:63], v[48:49], v[54:55]
	v_rsq_f32_e32 v54, v25
	ds_write_b128 v126, v[46:49] offset:24576
	s_mov_b64 s[98:99], exec
	s_mov_b32 exec_lo, 0xffff0000
	ds_read_b128 v[140:143], v126 offset:24320
	s_mov_b32 exec_lo, 0
	ds_read_b128 v[144:147], v126 offset:24064
	s_mov_b32 exec_hi, 0xffff0000
	ds_read_b128 v[148:151], v126 offset:23808
	s_mov_b64 exec, s[98:99]
	v_mov_b32_e32 v180, 1.0
	s_mov_b32 vcc_lo, 0xffff0000
	s_mov_b32 vcc_hi, -1
	s_waitcnt lgkmcnt(0)
	v_cndmask_b32_e32 v140, 1.0, v140, vcc
	v_cndmask_b32_e32 v141, 1.0, v141, vcc
	v_cndmask_b32_e32 v142, 1.0, v142, vcc
	v_cndmask_b32_e32 v143, 1.0, v143, vcc
	s_mov_b32 vcc_lo, 0
	s_nop 1
	v_cndmask_b32_e32 v144, 1.0, v144, vcc
	v_cndmask_b32_e32 v145, 1.0, v145, vcc
	v_cndmask_b32_e32 v146, 1.0, v146, vcc
	v_cndmask_b32_e32 v147, 1.0, v147, vcc
	s_mov_b32 vcc_hi, 0xffff0000
	s_nop 1
	v_cndmask_b32_e32 v148, 1.0, v148, vcc
	v_cndmask_b32_e32 v149, 1.0, v149, vcc
	v_cndmask_b32_e32 v150, 1.0, v150, vcc
	v_cndmask_b32_e32 v151, 1.0, v151, vcc
	v_pk_mul_f32 v[152:153], v[140:141], v[144:145]
	v_pk_mul_f32 v[154:155], v[142:143], v[146:147]
	v_pk_mul_f32 v[152:153], v[152:153], v[148:149]
	v_pk_mul_f32 v[154:155], v[154:155], v[150:151]
	v_pk_mul_f32 v[156:157], v[152:153], v[46:47]
	v_pk_mul_f32 v[158:159], v[154:155], v[48:49]
	v_rcp_f32_e32 v160, v156
	v_rcp_f32_e32 v161, v157
	v_rcp_f32_e32 v162, v158
	v_rcp_f32_e32 v163, v159
	s_nop 1
	v_cndmask_b32_e32 v160, v160, v180, vcc
	v_cndmask_b32_e32 v161, v161, v180, vcc
	v_cndmask_b32_e32 v162, v162, v180, vcc
	v_cndmask_b32_e32 v163, v163, v180, vcc
	s_mov_b32 exec_lo, 0
	s_mov_b32 exec_hi, 0xffff0000
	ds_write_b128 v126, v[156:159] offset:24576
	s_mov_b64 exec, s[98:99]
	v_pk_mul_f32 v[164:165], v[50:51], v[160:161]
	v_pk_mul_f32 v[166:167], v[52:53], v[162:163]
	ds_write_b128 v126, v[164:167] offset:16384
	v_pk_mul_f32 v[58:59], v[46:47], v[26:27]
	v_mul_f32_e32 v43, v64, v42
	v_pk_mul_f32 v[20:21], v[20:21], v[54:55] op_sel_hi:[1,0]
	v_pk_mul_f32 v[22:23], v[22:23], v[54:55] op_sel_hi:[1,0]
	v_mul_f32_e64 v46, v31, -v54
	v_pk_mul_f32 v[28:29], v[56:57], v[54:55] op_sel_hi:[1,0]
	v_pk_mul_f32 v[26:27], v[60:61], v[54:55] op_sel_hi:[1,0]
	v_pk_fma_f32 v[48:49], v[46:47], v[22:23], v[62:63] op_sel_hi:[0,1,1]
	v_pk_fma_f32 v[46:47], v[46:47], v[20:21], v[58:59] op_sel_hi:[0,1,1]
	v_pk_mul_f32 v[168:169], v[26:27], v[160:161]
	v_pk_mul_f32 v[170:171], v[28:29], v[162:163]
	ds_write_b128 v126, v[168:171] offset:32768
	v_mul_f32_e32 v172, v20, v152
	v_mul_f32_e32 v173, v21, v153
	v_mul_f32_e32 v174, v22, v154
	v_mul_f32_e32 v175, v23, v155
	v_mul_f32_e32 v176, v46, v152
	v_mul_f32_e32 v177, v47, v153
	v_mul_f32_e32 v178, v48, v154
	v_mul_f32_e32 v179, v49, v155
	v_add_u32_e32 v201, 0x2000, v126
	ds_write2_b32 v126, v172, v176 offset1:1
	ds_write2_b32 v126, v173, v177 offset0:2 offset1:3
	ds_write2_b32 v201, v174, v178 offset1:1
	ds_write2_b32 v201, v175, v179 offset0:2 offset1:3
	v_mul_f32_e32 v45, v64, v44
	v_add_u32_e32 v20, v124, v127
	v_mul_f32_e32 v31, v64, v30
	v_mul_f32_e32 v33, v64, v32
	v_lshl_add_u64 v[22:23], s[12:13], 0, v[16:17]
	ds_write_b128 v20, v[42:45] offset:40960
	ds_write_b128 v20, v[30:33] offset:40976
	s_and_saveexec_b64 s[14:15], s[0:1]
	s_cbranch_execz .LBB0_188
	global_store_dword v[22:23], v24, off
.LBB0_188:
	s_or_b64 exec, exec, s[14:15]
	v_add_co_u32_e32 v24, vcc, 0x18000, v14
	s_mov_b64 s[14:15], 0x18000
	s_nop 0
	v_addc_co_u32_e32 v25, vcc, 0, v15, vcc
	v_lshl_add_u64 v[16:17], v[14:15], 0, s[14:15]
	v_add_co_u32_e32 v14, vcc, 0x19000, v14
	global_load_dwordx2 v[24:25], v[24:25], off
	s_nop 0
	global_load_dwordx2 v[32:33], v[16:17], off offset:2048
	v_addc_co_u32_e32 v15, vcc, 0, v15, vcc
	global_load_dwordx2 v[54:55], v[14:15], off
	v_add_co_u32_e32 v14, vcc, 0x18000, v18
	v_lshl_add_u64 v[20:21], v[18:19], 0, s[14:15]
	s_nop 0
	v_addc_co_u32_e32 v15, vcc, 0, v19, vcc
	global_load_dwordx2 v[14:15], v[14:15], off
	s_nop 0
	global_load_dwordx2 v[18:19], v[20:21], off offset:2048
	s_waitcnt vmcnt(4)
	v_lshlrev_b32_e32 v50, 16, v25
	s_waitcnt vmcnt(3)
	v_and_b32_e32 v17, 0xffff0000, v32
	v_and_b32_e32 v51, 0xffff0000, v25
	s_waitcnt vmcnt(1)
	v_lshlrev_b32_e32 v16, 16, v14
	s_waitcnt vmcnt(0)
	v_lshlrev_b32_e32 v42, 16, v18
	v_and_b32_e32 v43, 0xffff0000, v18
	v_and_b32_e32 v14, 0xffff0000, v14
	v_exp_f32_e32 v26, v16
	v_lshlrev_b32_e32 v16, 16, v32
	v_pk_fma_f32 v[28:29], v[42:43], v[2:3], v[38:39]
	v_lshlrev_b32_e32 v44, 16, v15
	v_and_b32_e32 v45, 0xffff0000, v15
	v_exp_f32_e32 v27, v14
	v_lshlrev_b32_e32 v14, 16, v24
	v_and_b32_e32 v15, 0xffff0000, v24
	v_pk_mul_f32 v[30:31], v[28:29], v[16:17]
	v_lshlrev_b32_e32 v18, 16, v19
	v_pk_mul_f32 v[28:29], v[30:31], v[14:15]
	v_and_b32_e32 v19, 0xffff0000, v19
	v_fma_f32 v24, v28, v10, 0
	v_lshlrev_b32_e32 v32, 16, v33
	v_and_b32_e32 v33, 0xffff0000, v33
	v_pk_fma_f32 v[46:47], v[18:19], v[4:5], v[40:41]
	v_fmac_f32_e32 v24, v29, v11
	v_exp_f32_e32 v28, v44
	v_exp_f32_e32 v29, v45
	v_pk_mul_f32 v[44:45], v[8:9], v[32:33]
	v_pk_mul_f32 v[32:33], v[46:47], v[32:33]
	v_pk_mul_f32 v[20:21], v[6:7], v[16:17]
	v_pk_mul_f32 v[46:47], v[32:33], v[50:51]
	v_fma_f32 v48, v20, v20, 0
	v_fmac_f32_e32 v24, v46, v12
	v_fmac_f32_e32 v24, v47, v13
	v_pk_mul_f32 v[46:47], v[20:21], v[42:43]
	v_fma_f32 v17, v30, v14, 0
	v_fma_f32 v25, v46, v14, 0
	v_fmac_f32_e32 v48, v21, v21
	v_fmac_f32_e32 v17, v31, v15
	v_fmac_f32_e32 v25, v47, v15
	v_pk_mul_f32 v[18:19], v[44:45], v[18:19]
	v_fmac_f32_e32 v48, v44, v44
	v_fmac_f32_e32 v17, v32, v50
	v_fmac_f32_e32 v25, v18, v50
	v_fmac_f32_e32 v48, v45, v45
	v_fmac_f32_e32 v17, v33, v51
	v_fmac_f32_e32 v25, v19, v51
	s_nop 1
	v_add_f32_dpp v48, v48, v48 quad_perm:[1,0,3,2] row_mask:0xf bank_mask:0xf
	v_add_f32_dpp v24, v24, v24 quad_perm:[1,0,3,2] row_mask:0xf bank_mask:0xf
	v_add_f32_dpp v25, v25, v25 quad_perm:[1,0,3,2] row_mask:0xf bank_mask:0xf
	v_add_f32_dpp v17, v17, v17 quad_perm:[1,0,3,2] row_mask:0xf bank_mask:0xf
	v_add_f32_dpp v48, v48, v48 quad_perm:[2,3,0,1] row_mask:0xf bank_mask:0xf
	v_add_f32_dpp v24, v24, v24 quad_perm:[2,3,0,1] row_mask:0xf bank_mask:0xf
	v_add_f32_dpp v25, v25, v25 quad_perm:[2,3,0,1] row_mask:0xf bank_mask:0xf
	v_add_f32_dpp v17, v17, v17 quad_perm:[2,3,0,1] row_mask:0xf bank_mask:0xf
	v_add_f32_dpp v48, v48, v48 row_half_mirror row_mask:0xf bank_mask:0xf
	v_add_f32_dpp v24, v24, v24 row_half_mirror row_mask:0xf bank_mask:0xf
	v_add_f32_dpp v25, v25, v25 row_half_mirror row_mask:0xf bank_mask:0xf
	v_add_f32_dpp v17, v17, v17 row_half_mirror row_mask:0xf bank_mask:0xf
	v_add_f32_dpp v48, v48, v48 row_mirror row_mask:0xf bank_mask:0xf
	v_add_f32_dpp v24, v24, v24 row_mirror row_mask:0xf bank_mask:0xf
	v_add_f32_dpp v25, v25, v25 row_mirror row_mask:0xf bank_mask:0xf
	v_add_f32_dpp v17, v17, v17 row_mirror row_mask:0xf bank_mask:0xf
	s_nop 0
	v_pk_mul_f32 v[14:15], v[26:27], v[14:15]
	v_max_f32_e32 v16, v48, v48
	v_max_f32_e32 v16, 0x179abe15, v16
	v_rsq_f32_e32 v16, v16
	s_nop 0
	v_pk_mul_f32 v[42:43], v[20:21], v[16:17] op_sel_hi:[1,0]
	v_pk_mul_f32 v[44:45], v[44:45], v[16:17] op_sel_hi:[1,0]
	v_pk_mul_f32 v[48:49], v[18:19], v[16:17] op_sel_hi:[1,0]
	v_pk_mul_f32 v[46:47], v[46:47], v[16:17] op_sel_hi:[1,0]
	v_pk_mul_f32 v[18:19], v[28:29], v[50:51]
	v_mul_f32_e64 v16, v25, -v16
	v_pk_fma_f32 v[52:53], v[16:17], v[44:45], v[18:19] op_sel_hi:[0,1,1]
	v_pk_fma_f32 v[50:51], v[16:17], v[42:43], v[14:15] op_sel_hi:[0,1,1]
	v_and_b32_e32 v16, 0xffff0000, v55
	v_lshlrev_b32_e32 v14, 16, v55
	v_and_b32_e32 v20, 0xffff0000, v54
	v_lshlrev_b32_e32 v18, 16, v54
	v_mul_f32_e32 v19, v17, v18
	v_mul_f32_e32 v21, v17, v20
	v_add_u32_e32 v25, v124, v130
	v_mul_f32_e32 v15, v17, v14
	v_mul_f32_e32 v17, v17, v16
	ds_write_b128 v129, v[26:29] offset:24576
	s_mov_b64 s[98:99], exec
	s_mov_b32 exec_lo, 0xffff0000
	ds_read_b128 v[140:143], v129 offset:24320
	s_mov_b32 exec_lo, 0
	ds_read_b128 v[144:147], v129 offset:24064
	s_mov_b32 exec_hi, 0xffff0000
	ds_read_b128 v[148:151], v129 offset:23808
	s_mov_b64 exec, s[98:99]
	v_mov_b32_e32 v180, 1.0
	s_mov_b32 vcc_lo, 0xffff0000
	s_mov_b32 vcc_hi, -1
	s_waitcnt lgkmcnt(0)
	v_cndmask_b32_e32 v140, 1.0, v140, vcc
	v_cndmask_b32_e32 v141, 1.0, v141, vcc
	v_cndmask_b32_e32 v142, 1.0, v142, vcc
	v_cndmask_b32_e32 v143, 1.0, v143, vcc
	s_mov_b32 vcc_lo, 0
	s_nop 1
	v_cndmask_b32_e32 v144, 1.0, v144, vcc
	v_cndmask_b32_e32 v145, 1.0, v145, vcc
	v_cndmask_b32_e32 v146, 1.0, v146, vcc
	v_cndmask_b32_e32 v147, 1.0, v147, vcc
	s_mov_b32 vcc_hi, 0xffff0000
	s_nop 1
	v_cndmask_b32_e32 v148, 1.0, v148, vcc
	v_cndmask_b32_e32 v149, 1.0, v149, vcc
	v_cndmask_b32_e32 v150, 1.0, v150, vcc
	v_cndmask_b32_e32 v151, 1.0, v151, vcc
	v_pk_mul_f32 v[152:153], v[140:141], v[144:145]
	v_pk_mul_f32 v[154:155], v[142:143], v[146:147]
	v_pk_mul_f32 v[152:153], v[152:153], v[148:149]
	v_pk_mul_f32 v[154:155], v[154:155], v[150:151]
	v_pk_mul_f32 v[156:157], v[152:153], v[26:27]
	v_pk_mul_f32 v[158:159], v[154:155], v[28:29]
	v_rcp_f32_e32 v160, v156
	v_rcp_f32_e32 v161, v157
	v_rcp_f32_e32 v162, v158
	v_rcp_f32_e32 v163, v159
	s_nop 1
	v_cndmask_b32_e32 v160, v160, v180, vcc
	v_cndmask_b32_e32 v161, v161, v180, vcc
	v_cndmask_b32_e32 v162, v162, v180, vcc
	v_cndmask_b32_e32 v163, v163, v180, vcc
	s_mov_b32 exec_lo, 0
	s_mov_b32 exec_hi, 0xffff0000
	ds_write_b128 v129, v[156:159] offset:24576
	s_mov_b64 exec, s[98:99]
	v_pk_mul_f32 v[164:165], v[30:31], v[160:161]
	v_pk_mul_f32 v[166:167], v[32:33], v[162:163]
	ds_write_b128 v129, v[164:167] offset:16384
	v_pk_mul_f32 v[168:169], v[46:47], v[160:161]
	v_pk_mul_f32 v[170:171], v[48:49], v[162:163]
	ds_write_b128 v129, v[168:171] offset:32768
	v_mul_f32_e32 v172, v42, v152
	v_mul_f32_e32 v173, v43, v153
	v_mul_f32_e32 v174, v44, v154
	v_mul_f32_e32 v175, v45, v155
	v_mul_f32_e32 v176, v50, v152
	v_mul_f32_e32 v177, v51, v153
	v_mul_f32_e32 v178, v52, v154
	v_mul_f32_e32 v179, v53, v155
	v_add_u32_e32 v201, 0x2000, v129
	ds_write2_b32 v129, v172, v176 offset1:1
	ds_write2_b32 v129, v173, v177 offset0:2 offset1:3
	ds_write2_b32 v201, v174, v178 offset1:1
	ds_write2_b32 v201, v175, v179 offset0:2 offset1:3
	ds_write_b128 v25, v[18:21] offset:40960
	ds_write_b128 v25, v[14:17] offset:40976
	s_and_saveexec_b64 s[14:15], s[0:1]
	s_cbranch_execz .LBB0_190
	global_store_dword v[22:23], v24, off offset:1024
.LBB0_190:
	s_or_b64 exec, exec, s[14:15]
	v_lshl_add_u64 v[42:43], v[104:105], 0, s[10:11]
	v_lshl_add_u64 v[46:47], v[42:43], 0, 32
	s_movk_i32 s20, 0x1800
	v_mad_u64_u32 v[14:15], s[14:15], v46, s20, v[34:35]
	v_mad_i32_i24 v15, v47, s20, v15
	v_add_co_u32_e32 v18, vcc, s73, v14
	v_mad_u64_u32 v[16:17], s[14:15], v46, s20, v[36:37]
	s_nop 0
	v_addc_co_u32_e32 v19, vcc, 0, v15, vcc
	v_mad_i32_i24 v17, v47, s20, v17
	global_load_dwordx2 v[20:21], v[14:15], off
	global_load_dwordx2 v[22:23], v[14:15], off offset:2048
	global_load_dwordx2 v[54:55], v[18:19], off
	s_nop 0
	global_load_dwordx2 v[18:19], v[16:17], off
	global_load_dwordx2 v[24:25], v[16:17], off offset:2048
	s_mov_b64 s[14:15], 0x18000
	v_lshl_add_u64 v[26:27], v[14:15], 0, s[14:15]
	v_lshl_add_u64 v[28:29], v[16:17], 0, s[14:15]
	s_mov_b32 s14, 0x19000
	v_add_co_u32_e32 v14, vcc, s14, v14
	s_mov_b32 s14, 0x18000
	s_nop 0
	v_addc_co_u32_e32 v15, vcc, 0, v15, vcc
	global_load_dwordx2 v[50:51], v[14:15], off offset:-4096
	global_load_dwordx2 v[48:49], v[26:27], off offset:2048
	global_load_dwordx2 v[44:45], v[14:15], off
	v_add_co_u32_e32 v14, vcc, s14, v16
	s_waitcnt vmcnt(7)
	v_lshlrev_b32_e32 v60, 16, v20
	v_addc_co_u32_e32 v15, vcc, 0, v17, vcc
	global_load_dwordx2 v[56:57], v[14:15], off
	global_load_dwordx2 v[52:53], v[28:29], off offset:2048
	s_waitcnt vmcnt(5)
	v_lshlrev_b32_e32 v28, 16, v24
	v_and_b32_e32 v29, 0xffff0000, v24
	v_lshlrev_b32_e32 v14, 16, v18
	v_and_b32_e32 v15, 0xffff0000, v18
	v_lshlrev_b32_e32 v30, 16, v19
	v_and_b32_e32 v31, 0xffff0000, v19
	v_lshlrev_b32_e32 v16, 16, v22
	v_and_b32_e32 v17, 0xffff0000, v22
	v_pk_fma_f32 v[18:19], v[28:29], v[2:3], v[38:39]
	v_and_b32_e32 v61, 0xffff0000, v20
	v_pk_mul_f32 v[18:19], v[18:19], v[16:17]
	v_pk_mul_f32 v[26:27], v[6:7], v[16:17]
	v_pk_mul_f32 v[16:17], v[18:19], v[60:61]
	v_lshlrev_b32_e32 v24, 16, v25
	v_fma_f32 v58, v16, v10, 0
	v_and_b32_e32 v25, 0xffff0000, v25
	v_fmac_f32_e32 v58, v17, v11
	v_exp_f32_e32 v16, v30
	v_exp_f32_e32 v17, v31
	v_lshlrev_b32_e32 v62, 16, v21
	v_and_b32_e32 v63, 0xffff0000, v21
	v_lshlrev_b32_e32 v20, 16, v23
	v_and_b32_e32 v21, 0xffff0000, v23
	v_pk_fma_f32 v[30:31], v[24:25], v[4:5], v[40:41]
	v_pk_mul_f32 v[64:65], v[26:27], v[28:29]
	v_fma_f32 v32, v26, v26, 0
	v_fma_f32 v59, v18, v60, 0
	v_pk_mul_f32 v[22:23], v[8:9], v[20:21]
	v_pk_mul_f32 v[20:21], v[30:31], v[20:21]
	v_fma_f32 v67, v64, v60, 0
	v_fmac_f32_e32 v32, v27, v27
	v_fmac_f32_e32 v59, v19, v61
	v_pk_mul_f32 v[30:31], v[20:21], v[62:63]
	v_fmac_f32_e32 v67, v65, v61
	v_pk_mul_f32 v[24:25], v[22:23], v[24:25]
	v_fmac_f32_e32 v32, v22, v22
	v_fmac_f32_e32 v58, v30, v12
	v_fmac_f32_e32 v59, v20, v62
	v_fmac_f32_e32 v67, v24, v62
	v_fmac_f32_e32 v32, v23, v23
	v_fmac_f32_e32 v58, v31, v13
	v_fmac_f32_e32 v59, v21, v63
	v_fmac_f32_e32 v67, v25, v63
	s_waitcnt lgkmcnt(0)
	s_barrier
	s_nop 1
	v_add_f32_dpp v32, v32, v32 quad_perm:[1,0,3,2] row_mask:0xf bank_mask:0xf
	v_add_f32_dpp v58, v58, v58 quad_perm:[1,0,3,2] row_mask:0xf bank_mask:0xf
	v_add_f32_dpp v67, v67, v67 quad_perm:[1,0,3,2] row_mask:0xf bank_mask:0xf
	v_add_f32_dpp v59, v59, v59 quad_perm:[1,0,3,2] row_mask:0xf bank_mask:0xf
	v_add_f32_dpp v32, v32, v32 quad_perm:[2,3,0,1] row_mask:0xf bank_mask:0xf
	v_add_f32_dpp v58, v58, v58 quad_perm:[2,3,0,1] row_mask:0xf bank_mask:0xf
	v_add_f32_dpp v67, v67, v67 quad_perm:[2,3,0,1] row_mask:0xf bank_mask:0xf
	v_add_f32_dpp v59, v59, v59 quad_perm:[2,3,0,1] row_mask:0xf bank_mask:0xf
	v_add_f32_dpp v32, v32, v32 row_half_mirror row_mask:0xf bank_mask:0xf
	v_add_f32_dpp v58, v58, v58 row_half_mirror row_mask:0xf bank_mask:0xf
	v_add_f32_dpp v67, v67, v67 row_half_mirror row_mask:0xf bank_mask:0xf
	v_add_f32_dpp v59, v59, v59 row_half_mirror row_mask:0xf bank_mask:0xf
	v_add_f32_dpp v32, v32, v32 row_mirror row_mask:0xf bank_mask:0xf
	v_add_f32_dpp v58, v58, v58 row_mirror row_mask:0xf bank_mask:0xf
	v_add_f32_dpp v67, v67, v67 row_mirror row_mask:0xf bank_mask:0xf
	v_add_f32_dpp v59, v59, v59 row_mirror row_mask:0xf bank_mask:0xf
	s_nop 0
	v_exp_f32_e32 v14, v14
	v_max_f32_e32 v28, v32, v32
	v_max_f32_e32 v28, 0x179abe15, v28
	v_exp_f32_e32 v15, v15
	v_rsq_f32_e32 v66, v28
	s_nop 0
	v_pk_mul_f32 v[30:31], v[26:27], v[66:67] op_sel_hi:[1,0]
	v_pk_mul_f32 v[32:33], v[22:23], v[66:67] op_sel_hi:[1,0]
	v_pk_mul_f32 v[28:29], v[24:25], v[66:67] op_sel_hi:[1,0]
	v_pk_mul_f32 v[22:23], v[14:15], v[60:61]
	v_pk_mul_f32 v[24:25], v[16:17], v[62:63]
	v_mul_f32_e64 v60, v67, -v66
	v_pk_mul_f32 v[26:27], v[64:65], v[66:67] op_sel_hi:[1,0]
	v_pk_fma_f32 v[24:25], v[60:61], v[32:33], v[24:25] op_sel_hi:[0,1,1]
	v_pk_fma_f32 v[22:23], v[60:61], v[30:31], v[22:23] op_sel_hi:[0,1,1]
	v_and_b32_e32 v62, 0xffff0000, v55
	v_lshlrev_b32_e32 v60, 16, v55
	v_and_b32_e32 v66, 0xffff0000, v54
	v_lshlrev_b32_e32 v64, 16, v54
	ds_write_b128 v133, v[14:17] offset:24576
	s_mov_b64 s[98:99], exec
	s_mov_b32 exec_lo, 0xffff0000
	ds_read_b128 v[140:143], v133 offset:24320
	s_mov_b32 exec_lo, 0
	ds_read_b128 v[144:147], v133 offset:24064
	s_mov_b32 exec_hi, 0xffff0000
	ds_read_b128 v[148:151], v133 offset:23808
	s_mov_b64 exec, s[98:99]
	v_mov_b32_e32 v180, 1.0
	s_mov_b32 vcc_lo, 0xffff0000
	s_mov_b32 vcc_hi, -1
	s_waitcnt lgkmcnt(0)
	v_cndmask_b32_e32 v140, 1.0, v140, vcc
	v_cndmask_b32_e32 v141, 1.0, v141, vcc
	v_cndmask_b32_e32 v142, 1.0, v142, vcc
	v_cndmask_b32_e32 v143, 1.0, v143, vcc
	s_mov_b32 vcc_lo, 0
	s_nop 1
	v_cndmask_b32_e32 v144, 1.0, v144, vcc
	v_cndmask_b32_e32 v145, 1.0, v145, vcc
	v_cndmask_b32_e32 v146, 1.0, v146, vcc
	v_cndmask_b32_e32 v147, 1.0, v147, vcc
	s_mov_b32 vcc_hi, 0xffff0000
	s_nop 1
	v_cndmask_b32_e32 v148, 1.0, v148, vcc
	v_cndmask_b32_e32 v149, 1.0, v149, vcc
	v_cndmask_b32_e32 v150, 1.0, v150, vcc
	v_cndmask_b32_e32 v151, 1.0, v151, vcc
	v_pk_mul_f32 v[152:153], v[140:141], v[144:145]
	v_pk_mul_f32 v[154:155], v[142:143], v[146:147]
	v_pk_mul_f32 v[152:153], v[152:153], v[148:149]
	v_pk_mul_f32 v[154:155], v[154:155], v[150:151]
	v_pk_mul_f32 v[156:157], v[152:153], v[14:15]
	v_pk_mul_f32 v[158:159], v[154:155], v[16:17]
	v_rcp_f32_e32 v160, v156
	v_rcp_f32_e32 v161, v157
	v_rcp_f32_e32 v162, v158
	v_rcp_f32_e32 v163, v159
	s_nop 1
	v_cndmask_b32_e32 v160, v160, v180, vcc
	v_cndmask_b32_e32 v161, v161, v180, vcc
	v_cndmask_b32_e32 v162, v162, v180, vcc
	v_cndmask_b32_e32 v163, v163, v180, vcc
	s_mov_b32 exec_lo, 0
	s_mov_b32 exec_hi, 0xffff0000
	ds_write_b128 v133, v[156:159] offset:24576
	s_mov_b64 exec, s[98:99]
	v_pk_mul_f32 v[164:165], v[18:19], v[160:161]
	v_pk_mul_f32 v[166:167], v[20:21], v[162:163]
	ds_write_b128 v133, v[164:167] offset:16384
	v_pk_mul_f32 v[168:169], v[26:27], v[160:161]
	v_pk_mul_f32 v[170:171], v[28:29], v[162:163]
	ds_write_b128 v133, v[168:171] offset:32768
	v_mul_f32_e32 v172, v30, v152
	v_mul_f32_e32 v173, v31, v153
	v_mul_f32_e32 v174, v32, v154
	v_mul_f32_e32 v175, v33, v155
	v_mul_f32_e32 v176, v22, v152
	v_mul_f32_e32 v177, v23, v153
	v_mul_f32_e32 v178, v24, v154
	v_mul_f32_e32 v179, v25, v155
	v_add_u32_e32 v201, 0x2000, v133
	ds_write2_b32 v133, v172, v176 offset1:1
	ds_write2_b32 v133, v173, v177 offset0:2 offset1:3
	ds_write2_b32 v201, v174, v178 offset1:1
	ds_write2_b32 v201, v175, v179 offset0:2 offset1:3
	v_mul_f32_e32 v65, v59, v64
	v_mul_f32_e32 v67, v59, v66
	v_add_u32_e32 v14, v132, v127
	v_mul_f32_e32 v61, v59, v60
	v_mul_f32_e32 v63, v59, v62
	ds_write_b128 v14, v[64:67]
	ds_write_b128 v14, v[60:63] offset:16
	v_lshlrev_b64 v[14:15], 6, v[46:47]
	v_lshl_add_u64 v[14:15], s[12:13], 0, v[14:15]
	s_and_saveexec_b64 s[12:13], s[0:1]
	s_cbranch_execz .LBB0_192
	global_store_dword v[14:15], v58, off
.LBB0_192:
	s_or_b64 exec, exec, s[12:13]
	s_waitcnt vmcnt(1)
	v_lshlrev_b32_e32 v16, 16, v56
	s_waitcnt vmcnt(0)
	v_lshlrev_b32_e32 v20, 16, v52
	v_and_b32_e32 v21, 0xffff0000, v52
	v_exp_f32_e32 v18, v16
	v_lshlrev_b32_e32 v16, 16, v48
	v_and_b32_e32 v17, 0xffff0000, v48
	v_pk_fma_f32 v[22:23], v[20:21], v[2:3], v[38:39]
	v_lshlrev_b32_e32 v46, 16, v50
	v_and_b32_e32 v47, 0xffff0000, v50
	v_pk_mul_f32 v[22:23], v[22:23], v[16:17]
	v_pk_mul_f32 v[26:27], v[6:7], v[16:17]
	v_pk_mul_f32 v[16:17], v[22:23], v[46:47]
	v_lshlrev_b32_e32 v30, 16, v53
	v_and_b32_e32 v31, 0xffff0000, v53
	v_fma_f32 v16, v16, v10, 0
	v_lshlrev_b32_e32 v24, 16, v49
	v_and_b32_e32 v25, 0xffff0000, v49
	v_pk_fma_f32 v[32:33], v[30:31], v[4:5], v[40:41]
	v_pk_mul_f32 v[48:49], v[26:27], v[20:21]
	v_and_b32_e32 v19, 0xffff0000, v56
	v_fma_f32 v56, v26, v26, 0
	v_fma_f32 v58, v22, v46, 0
	v_fmac_f32_e32 v16, v17, v11
	v_lshlrev_b32_e32 v50, 16, v51
	v_and_b32_e32 v51, 0xffff0000, v51
	v_pk_mul_f32 v[28:29], v[8:9], v[24:25]
	v_pk_mul_f32 v[24:25], v[32:33], v[24:25]
	v_fma_f32 v17, v48, v46, 0
	v_fmac_f32_e32 v56, v27, v27
	v_fmac_f32_e32 v58, v23, v47
	v_pk_mul_f32 v[32:33], v[24:25], v[50:51]
	v_fmac_f32_e32 v17, v49, v47
	v_pk_mul_f32 v[30:31], v[28:29], v[30:31]
	v_fmac_f32_e32 v56, v28, v28
	v_fmac_f32_e32 v16, v32, v12
	v_fmac_f32_e32 v58, v24, v50
	v_fmac_f32_e32 v17, v30, v50
	v_fmac_f32_e32 v56, v29, v29
	v_fmac_f32_e32 v16, v33, v13
	v_fmac_f32_e32 v58, v25, v51
	v_fmac_f32_e32 v17, v31, v51
	s_nop 1
	v_add_f32_dpp v56, v56, v56 quad_perm:[1,0,3,2] row_mask:0xf bank_mask:0xf
	v_add_f32_dpp v16, v16, v16 quad_perm:[1,0,3,2] row_mask:0xf bank_mask:0xf
	v_add_f32_dpp v17, v17, v17 quad_perm:[1,0,3,2] row_mask:0xf bank_mask:0xf
	v_add_f32_dpp v58, v58, v58 quad_perm:[1,0,3,2] row_mask:0xf bank_mask:0xf
	v_add_f32_dpp v56, v56, v56 quad_perm:[2,3,0,1] row_mask:0xf bank_mask:0xf
	v_add_f32_dpp v16, v16, v16 quad_perm:[2,3,0,1] row_mask:0xf bank_mask:0xf
	v_add_f32_dpp v17, v17, v17 quad_perm:[2,3,0,1] row_mask:0xf bank_mask:0xf
	v_add_f32_dpp v58, v58, v58 quad_perm:[2,3,0,1] row_mask:0xf bank_mask:0xf
	v_add_f32_dpp v56, v56, v56 row_half_mirror row_mask:0xf bank_mask:0xf
	v_add_f32_dpp v16, v16, v16 row_half_mirror row_mask:0xf bank_mask:0xf
	v_add_f32_dpp v17, v17, v17 row_half_mirror row_mask:0xf bank_mask:0xf
	v_add_f32_dpp v58, v58, v58 row_half_mirror row_mask:0xf bank_mask:0xf
	v_add_f32_dpp v56, v56, v56 row_mirror row_mask:0xf bank_mask:0xf
	v_add_f32_dpp v16, v16, v16 row_mirror row_mask:0xf bank_mask:0xf
	v_add_f32_dpp v17, v17, v17 row_mirror row_mask:0xf bank_mask:0xf
	v_add_f32_dpp v58, v58, v58 row_mirror row_mask:0xf bank_mask:0xf
	s_nop 0
	v_lshlrev_b32_e32 v54, 16, v57
	v_max_f32_e32 v20, v56, v56
	v_and_b32_e32 v55, 0xffff0000, v57
	v_max_f32_e32 v20, 0x179abe15, v20
	v_rsq_f32_e32 v52, v20
	v_exp_f32_e32 v19, v19
	v_exp_f32_e32 v20, v54
	v_exp_f32_e32 v21, v55
	v_pk_mul_f32 v[26:27], v[26:27], v[52:53] op_sel_hi:[1,0]
	v_pk_mul_f32 v[28:29], v[28:29], v[52:53] op_sel_hi:[1,0]
	v_pk_mul_f32 v[32:33], v[30:31], v[52:53] op_sel_hi:[1,0]
	v_pk_mul_f32 v[30:31], v[48:49], v[52:53] op_sel_hi:[1,0]
	v_pk_mul_f32 v[46:47], v[18:19], v[46:47]
	v_pk_mul_f32 v[48:49], v[20:21], v[50:51]
	v_mul_f32_e64 v50, v17, -v52
	v_pk_fma_f32 v[48:49], v[50:51], v[28:29], v[48:49] op_sel_hi:[0,1,1]
	v_pk_fma_f32 v[46:47], v[50:51], v[26:27], v[46:47] op_sel_hi:[0,1,1]
	v_and_b32_e32 v52, 0xffff0000, v45
	v_lshlrev_b32_e32 v50, 16, v45
	v_and_b32_e32 v56, 0xffff0000, v44
	v_lshlrev_b32_e32 v54, 16, v44
	v_mul_f32_e32 v55, v58, v54
	v_mul_f32_e32 v57, v58, v56
	v_add_u32_e32 v17, v132, v130
	v_mul_f32_e32 v51, v58, v50
	v_mul_f32_e32 v53, v58, v52
	ds_write_b128 v134, v[18:21] offset:24576
	s_mov_b64 s[98:99], exec
	s_mov_b32 exec_lo, 0xffff0000
	ds_read_b128 v[140:143], v134 offset:24320
	s_mov_b32 exec_lo, 0
	ds_read_b128 v[144:147], v134 offset:24064
	s_mov_b32 exec_hi, 0xffff0000
	ds_read_b128 v[148:151], v134 offset:23808
	s_mov_b64 exec, s[98:99]
	v_mov_b32_e32 v180, 1.0
	s_mov_b32 vcc_lo, 0xffff0000
	s_mov_b32 vcc_hi, -1
	s_waitcnt lgkmcnt(0)
	v_cndmask_b32_e32 v140, 1.0, v140, vcc
	v_cndmask_b32_e32 v141, 1.0, v141, vcc
	v_cndmask_b32_e32 v142, 1.0, v142, vcc
	v_cndmask_b32_e32 v143, 1.0, v143, vcc
	s_mov_b32 vcc_lo, 0
	s_nop 1
	v_cndmask_b32_e32 v144, 1.0, v144, vcc
	v_cndmask_b32_e32 v145, 1.0, v145, vcc
	v_cndmask_b32_e32 v146, 1.0, v146, vcc
	v_cndmask_b32_e32 v147, 1.0, v147, vcc
	s_mov_b32 vcc_hi, 0xffff0000
	s_nop 1
	v_cndmask_b32_e32 v148, 1.0, v148, vcc
	v_cndmask_b32_e32 v149, 1.0, v149, vcc
	v_cndmask_b32_e32 v150, 1.0, v150, vcc
	v_cndmask_b32_e32 v151, 1.0, v151, vcc
	v_pk_mul_f32 v[152:153], v[140:141], v[144:145]
	v_pk_mul_f32 v[154:155], v[142:143], v[146:147]
	v_pk_mul_f32 v[152:153], v[152:153], v[148:149]
	v_pk_mul_f32 v[154:155], v[154:155], v[150:151]
	v_pk_mul_f32 v[156:157], v[152:153], v[18:19]
	v_pk_mul_f32 v[158:159], v[154:155], v[20:21]
	v_rcp_f32_e32 v160, v156
	v_rcp_f32_e32 v161, v157
	v_rcp_f32_e32 v162, v158
	v_rcp_f32_e32 v163, v159
	s_nop 1
	v_cndmask_b32_e32 v160, v160, v180, vcc
	v_cndmask_b32_e32 v161, v161, v180, vcc
	v_cndmask_b32_e32 v162, v162, v180, vcc
	v_cndmask_b32_e32 v163, v163, v180, vcc
	s_mov_b32 exec_lo, 0
	s_mov_b32 exec_hi, 0xffff0000
	ds_write_b128 v134, v[156:159] offset:24576
	s_mov_b64 exec, s[98:99]
	v_pk_mul_f32 v[164:165], v[22:23], v[160:161]
	v_pk_mul_f32 v[166:167], v[24:25], v[162:163]
	ds_write_b128 v134, v[164:167] offset:16384
	v_pk_mul_f32 v[168:169], v[30:31], v[160:161]
	v_pk_mul_f32 v[170:171], v[32:33], v[162:163]
	ds_write_b128 v134, v[168:171] offset:32768
	v_mul_f32_e32 v172, v26, v152
	v_mul_f32_e32 v173, v27, v153
	v_mul_f32_e32 v174, v28, v154
	v_mul_f32_e32 v175, v29, v155
	v_mul_f32_e32 v176, v46, v152
	v_mul_f32_e32 v177, v47, v153
	v_mul_f32_e32 v178, v48, v154
	v_mul_f32_e32 v179, v49, v155
	v_add_u32_e32 v201, 0x2000, v134
	ds_write2_b32 v134, v172, v176 offset1:1
	ds_write2_b32 v134, v173, v177 offset0:2 offset1:3
	ds_write2_b32 v201, v174, v178 offset1:1
	ds_write2_b32 v201, v175, v179 offset0:2 offset1:3
	ds_write_b128 v17, v[54:57]
	ds_write_b128 v17, v[50:53] offset:16
	s_and_saveexec_b64 s[12:13], s[0:1]
	s_cbranch_execz .LBB0_194
	global_store_dword v[14:15], v16, off offset:1024

.LBB0_197:
	s_andn2_b32 s2, 0x400, s13
	v_lshl_add_u32 v48, s2, 2, v131
	v_readlane_b32 s20, v248, 7
	ds_read_b128 v[48:51], v48
	v_readlane_b32 s21, v248, 8
	s_waitcnt lgkmcnt(0)
	v_cvt_pk_bf16_f32 v48, v48, v49
	v_cvt_pk_bf16_f32 v49, v50, v51
	s_cmp_eq_u32 s12, 64
	v_readlane_b32 s22, v248, 9
	v_lshl_add_u64 v[50:51], s[20:21], 0, v[18:19]
	v_readlane_b32 s23, v248, 10
	global_store_dwordx2 v[50:51], v[48:49], off
	s_cbranch_scc1 .LBB0_196
	s_waitcnt vmcnt(7)
	v_lshlrev_b32_e32 v60, 16, v44
	v_and_b32_e32 v61, 0xffff0000, v44
	v_lshlrev_b32_e32 v52, 16, v32
	v_and_b32_e32 v53, 0xffff0000, v32
	v_pk_fma_f32 v[54:55], v[60:61], v[2:3], v[38:39]
	v_lshlrev_b32_e32 v50, 16, v46
	v_and_b32_e32 v51, 0xffff0000, v46
	v_lshlrev_b32_e32 v69, 16, v47
	v_and_b32_e32 v70, 0xffff0000, v47
	v_lshlrev_b32_e32 v46, 16, v42
	v_and_b32_e32 v47, 0xffff0000, v42
	v_pk_mul_f32 v[54:55], v[54:55], v[52:53]
	v_pk_mul_f32 v[58:59], v[6:7], v[52:53]
	v_pk_mul_f32 v[52:53], v[54:55], v[46:47]
	v_lshlrev_b32_e32 v44, 16, v45
	v_fma_f32 v32, v52, v10, 0
	v_and_b32_e32 v45, 0xffff0000, v45
	v_fmac_f32_e32 v32, v53, v11
	v_lshlrev_b32_e32 v62, 16, v43
	v_and_b32_e32 v63, 0xffff0000, v43
	v_lshlrev_b32_e32 v42, 16, v33
	v_and_b32_e32 v43, 0xffff0000, v33
	v_pk_fma_f32 v[52:53], v[44:45], v[4:5], v[40:41]
	v_pk_mul_f32 v[66:67], v[58:59], v[60:61]
	v_fma_f32 v68, v58, v58, 0
	v_fma_f32 v74, v54, v46, 0
	v_pk_mul_f32 v[64:65], v[8:9], v[42:43]
	v_pk_mul_f32 v[56:57], v[52:53], v[42:43]
	v_fma_f32 v33, v66, v46, 0
	v_fmac_f32_e32 v68, v59, v59
	v_fmac_f32_e32 v74, v55, v47
	v_pk_mul_f32 v[42:43], v[56:57], v[62:63]
	v_fmac_f32_e32 v33, v67, v47
	v_pk_mul_f32 v[60:61], v[64:65], v[44:45]
	v_fmac_f32_e32 v68, v64, v64
	v_fmac_f32_e32 v32, v42, v12
	v_fmac_f32_e32 v74, v56, v62
	v_fmac_f32_e32 v33, v60, v62
	v_fmac_f32_e32 v68, v65, v65
	v_fmac_f32_e32 v32, v43, v13
	v_fmac_f32_e32 v74, v57, v63
	v_fmac_f32_e32 v33, v61, v63
	s_nop 1
	v_add_f32_dpp v68, v68, v68 quad_perm:[1,0,3,2] row_mask:0xf bank_mask:0xf
	v_add_f32_dpp v32, v32, v32 quad_perm:[1,0,3,2] row_mask:0xf bank_mask:0xf
	v_add_f32_dpp v33, v33, v33 quad_perm:[1,0,3,2] row_mask:0xf bank_mask:0xf
	v_add_f32_dpp v74, v74, v74 quad_perm:[1,0,3,2] row_mask:0xf bank_mask:0xf
	v_add_f32_dpp v68, v68, v68 quad_perm:[2,3,0,1] row_mask:0xf bank_mask:0xf
	v_add_f32_dpp v32, v32, v32 quad_perm:[2,3,0,1] row_mask:0xf bank_mask:0xf
	v_add_f32_dpp v33, v33, v33 quad_perm:[2,3,0,1] row_mask:0xf bank_mask:0xf
	v_add_f32_dpp v74, v74, v74 quad_perm:[2,3,0,1] row_mask:0xf bank_mask:0xf
	v_add_f32_dpp v68, v68, v68 row_half_mirror row_mask:0xf bank_mask:0xf
	v_add_f32_dpp v32, v32, v32 row_half_mirror row_mask:0xf bank_mask:0xf
	v_add_f32_dpp v33, v33, v33 row_half_mirror row_mask:0xf bank_mask:0xf
	v_add_f32_dpp v74, v74, v74 row_half_mirror row_mask:0xf bank_mask:0xf
	v_add_f32_dpp v68, v68, v68 row_mirror row_mask:0xf bank_mask:0xf
	v_add_f32_dpp v32, v32, v32 row_mirror row_mask:0xf bank_mask:0xf
	v_add_f32_dpp v33, v33, v33 row_mirror row_mask:0xf bank_mask:0xf
	v_add_f32_dpp v74, v74, v74 row_mirror row_mask:0xf bank_mask:0xf
	s_nop 0
	v_exp_f32_e32 v50, v50
	v_max_f32_e32 v42, v68, v68
	v_max_f32_e32 v42, 0x179abe15, v42
	v_rsq_f32_e32 v68, v42
	v_exp_f32_e32 v51, v51
	v_exp_f32_e32 v52, v69
	v_exp_f32_e32 v53, v70
	s_bitcmp1_b32 s12, 0
	s_cselect_b32 s2, 0xe000, 0
	v_readlane_b32 s3, v251, 27
	s_add_i32 s2, s3, s2
	v_add_u32_e32 v49, s2, v122
	v_pk_mul_f32 v[42:43], v[58:59], v[68:69] op_sel_hi:[1,0]
	v_pk_mul_f32 v[44:45], v[64:65], v[68:69] op_sel_hi:[1,0]
	v_pk_mul_f32 v[58:59], v[66:67], v[68:69] op_sel_hi:[1,0]
	v_pk_mul_f32 v[46:47], v[50:51], v[46:47]
	v_pk_mul_f32 v[62:63], v[52:53], v[62:63]
	v_mul_f32_e64 v66, v33, -v68
	v_add_u32_e32 v48, s2, v123
	v_pk_mul_f32 v[60:61], v[60:61], v[68:69] op_sel_hi:[1,0]
	v_pk_fma_f32 v[64:65], v[66:67], v[44:45], v[62:63] op_sel_hi:[0,1,1]
	v_pk_fma_f32 v[62:63], v[66:67], v[42:43], v[46:47] op_sel_hi:[0,1,1]
	s_waitcnt vmcnt(4)
	v_and_b32_e32 v68, 0xffff0000, v31
	v_lshlrev_b32_e32 v66, 16, v31
	v_and_b32_e32 v72, 0xffff0000, v30
	v_lshlrev_b32_e32 v70, 16, v30
	v_add_u32_e32 v30, v49, v125
	ds_write_b128 v30, v[50:53] offset:24576
	s_mov_b64 s[98:99], exec
	s_mov_b32 exec_lo, 0xffff0000
	ds_read_b128 v[140:143], v30 offset:24320
	s_mov_b32 exec_lo, 0
	ds_read_b128 v[144:147], v30 offset:24064
	s_mov_b32 exec_hi, 0xffff0000
	ds_read_b128 v[148:151], v30 offset:23808
	s_mov_b64 exec, s[98:99]
	v_mov_b32_e32 v180, 1.0
	s_mov_b32 vcc_lo, 0xffff0000
	s_mov_b32 vcc_hi, -1
	s_waitcnt lgkmcnt(0)
	v_cndmask_b32_e32 v140, 1.0, v140, vcc
	v_cndmask_b32_e32 v141, 1.0, v141, vcc
	v_cndmask_b32_e32 v142, 1.0, v142, vcc
	v_cndmask_b32_e32 v143, 1.0, v143, vcc
	s_mov_b32 vcc_lo, 0
	s_nop 1
	v_cndmask_b32_e32 v144, 1.0, v144, vcc
	v_cndmask_b32_e32 v145, 1.0, v145, vcc
	v_cndmask_b32_e32 v146, 1.0, v146, vcc
	v_cndmask_b32_e32 v147, 1.0, v147, vcc
	s_mov_b32 vcc_hi, 0xffff0000
	s_nop 1
	v_cndmask_b32_e32 v148, 1.0, v148, vcc
	v_cndmask_b32_e32 v149, 1.0, v149, vcc
	v_cndmask_b32_e32 v150, 1.0, v150, vcc
	v_cndmask_b32_e32 v151, 1.0, v151, vcc
	v_pk_mul_f32 v[152:153], v[140:141], v[144:145]
	v_pk_mul_f32 v[154:155], v[142:143], v[146:147]
	v_pk_mul_f32 v[152:153], v[152:153], v[148:149]
	v_pk_mul_f32 v[154:155], v[154:155], v[150:151]
	v_pk_mul_f32 v[156:157], v[152:153], v[50:51]
	v_pk_mul_f32 v[158:159], v[154:155], v[52:53]
	v_rcp_f32_e32 v160, v156
	v_rcp_f32_e32 v161, v157
	v_rcp_f32_e32 v162, v158
	v_rcp_f32_e32 v163, v159
	s_nop 1
	v_cndmask_b32_e32 v160, v160, v180, vcc
	v_cndmask_b32_e32 v161, v161, v180, vcc
	v_cndmask_b32_e32 v162, v162, v180, vcc
	v_cndmask_b32_e32 v163, v163, v180, vcc
	s_mov_b32 exec_lo, 0
	s_mov_b32 exec_hi, 0xffff0000
	ds_write_b128 v30, v[156:159] offset:24576
	s_mov_b64 exec, s[98:99]
	v_pk_mul_f32 v[164:165], v[54:55], v[160:161]
	v_pk_mul_f32 v[166:167], v[56:57], v[162:163]
	ds_write_b128 v30, v[164:167] offset:16384
	v_pk_mul_f32 v[168:169], v[58:59], v[160:161]
	v_pk_mul_f32 v[170:171], v[60:61], v[162:163]
	ds_write_b128 v30, v[168:171] offset:32768
	v_mul_f32_e32 v172, v42, v152
	v_mul_f32_e32 v173, v43, v153
	v_mul_f32_e32 v174, v44, v154
	v_mul_f32_e32 v175, v45, v155
	v_mul_f32_e32 v176, v62, v152
	v_mul_f32_e32 v177, v63, v153
	v_mul_f32_e32 v178, v64, v154
	v_mul_f32_e32 v179, v65, v155
	v_add_u32_e32 v201, 0x2000, v30
	ds_write2_b32 v30, v172, v176 offset1:1
	ds_write2_b32 v30, v173, v177 offset0:2 offset1:3
	ds_write2_b32 v201, v174, v178 offset1:1
	ds_write2_b32 v201, v175, v179 offset0:2 offset1:3
	v_add_u32_e32 v30, v48, v127
	v_mul_f32_e32 v71, v74, v70
	v_mul_f32_e32 v73, v74, v72
	v_mul_f32_e32 v67, v74, v66
	v_mul_f32_e32 v69, v74, v68
	ds_write_b128 v30, v[70:73] offset:40960
	ds_write_b128 v30, v[66:69] offset:40976
	v_lshl_add_u64 v[30:31], s[20:21], 0, v[16:17]
	s_and_saveexec_b64 s[2:3], s[0:1]
	s_cbranch_execz .LBB0_200
	v_add_co_u32_e32 v42, vcc, 0x15d01000, v30
	s_nop 1
	v_addc_co_u32_e32 v43, vcc, 0, v31, vcc
	global_store_dword v[42:43], v32, off
.LBB0_200:
	s_or_b64 exec, exec, s[2:3]
	s_waitcnt vmcnt(2)
	v_lshlrev_b32_e32 v32, 16, v28
	s_waitcnt vmcnt(1)
	v_lshlrev_b32_e32 v44, 16, v26
	v_and_b32_e32 v45, 0xffff0000, v26
	v_exp_f32_e32 v42, v32
	v_lshlrev_b32_e32 v32, 16, v24
	v_and_b32_e32 v33, 0xffff0000, v24
	v_pk_fma_f32 v[50:51], v[44:45], v[2:3], v[38:39]
	v_and_b32_e32 v43, 0xffff0000, v28
	v_lshlrev_b32_e32 v61, 16, v29
	v_and_b32_e32 v62, 0xffff0000, v29
	v_lshlrev_b32_e32 v28, 16, v22
	v_and_b32_e32 v29, 0xffff0000, v22
	v_pk_mul_f32 v[50:51], v[50:51], v[32:33]
	v_pk_mul_f32 v[46:47], v[6:7], v[32:33]
	v_pk_mul_f32 v[32:33], v[50:51], v[28:29]
	v_lshlrev_b32_e32 v26, 16, v27
	v_and_b32_e32 v27, 0xffff0000, v27
	v_fma_f32 v22, v32, v10, 0
	v_lshlrev_b32_e32 v24, 16, v25
	v_and_b32_e32 v25, 0xffff0000, v25
	v_pk_fma_f32 v[52:53], v[26:27], v[4:5], v[40:41]
	v_pk_mul_f32 v[58:59], v[46:47], v[44:45]
	v_fma_f32 v60, v46, v46, 0
	v_fma_f32 v65, v50, v28, 0
	v_fmac_f32_e32 v22, v33, v11
	v_lshlrev_b32_e32 v32, 16, v23
	v_and_b32_e32 v33, 0xffff0000, v23
	v_pk_mul_f32 v[54:55], v[8:9], v[24:25]
	v_pk_mul_f32 v[52:53], v[52:53], v[24:25]
	v_fma_f32 v23, v58, v28, 0
	v_fmac_f32_e32 v60, v47, v47
	v_fmac_f32_e32 v65, v51, v29
	v_pk_mul_f32 v[24:25], v[52:53], v[32:33]
	v_fmac_f32_e32 v23, v59, v29
	v_pk_mul_f32 v[56:57], v[54:55], v[26:27]
	v_fmac_f32_e32 v60, v54, v54
	v_fmac_f32_e32 v22, v24, v12
	v_fmac_f32_e32 v65, v52, v32
	v_fmac_f32_e32 v23, v56, v32
	v_fmac_f32_e32 v60, v55, v55
	v_fmac_f32_e32 v22, v25, v13
	v_fmac_f32_e32 v65, v53, v33
	v_fmac_f32_e32 v23, v57, v33
	s_nop 1
	v_add_f32_dpp v60, v60, v60 quad_perm:[1,0,3,2] row_mask:0xf bank_mask:0xf
	v_add_f32_dpp v22, v22, v22 quad_perm:[1,0,3,2] row_mask:0xf bank_mask:0xf
	v_add_f32_dpp v23, v23, v23 quad_perm:[1,0,3,2] row_mask:0xf bank_mask:0xf
	v_add_f32_dpp v65, v65, v65 quad_perm:[1,0,3,2] row_mask:0xf bank_mask:0xf
	v_add_f32_dpp v60, v60, v60 quad_perm:[2,3,0,1] row_mask:0xf bank_mask:0xf
	v_add_f32_dpp v22, v22, v22 quad_perm:[2,3,0,1] row_mask:0xf bank_mask:0xf
	v_add_f32_dpp v23, v23, v23 quad_perm:[2,3,0,1] row_mask:0xf bank_mask:0xf
	v_add_f32_dpp v65, v65, v65 quad_perm:[2,3,0,1] row_mask:0xf bank_mask:0xf
	v_add_f32_dpp v60, v60, v60 row_half_mirror row_mask:0xf bank_mask:0xf
	v_add_f32_dpp v22, v22, v22 row_half_mirror row_mask:0xf bank_mask:0xf
	v_add_f32_dpp v23, v23, v23 row_half_mirror row_mask:0xf bank_mask:0xf
	v_add_f32_dpp v65, v65, v65 row_half_mirror row_mask:0xf bank_mask:0xf
	v_add_f32_dpp v60, v60, v60 row_mirror row_mask:0xf bank_mask:0xf
	v_add_f32_dpp v22, v22, v22 row_mirror row_mask:0xf bank_mask:0xf
	v_add_f32_dpp v23, v23, v23 row_mirror row_mask:0xf bank_mask:0xf
	v_add_f32_dpp v65, v65, v65 row_mirror row_mask:0xf bank_mask:0xf
	s_nop 0
	v_exp_f32_e32 v43, v43
	v_max_f32_e32 v24, v60, v60
	v_max_f32_e32 v24, 0x179abe15, v24
	v_rsq_f32_e32 v60, v24
	v_exp_f32_e32 v44, v61
	v_exp_f32_e32 v45, v62
	v_pk_mul_f32 v[28:29], v[42:43], v[28:29]
	v_pk_mul_f32 v[24:25], v[46:47], v[60:61] op_sel_hi:[1,0]
	v_pk_mul_f32 v[26:27], v[54:55], v[60:61] op_sel_hi:[1,0]
	v_pk_mul_f32 v[32:33], v[44:45], v[32:33]
	v_mul_f32_e64 v46, v23, -v60
	v_and_b32_e32 v64, 0xffff0000, v21
	v_lshlrev_b32_e32 v62, 16, v21
	v_and_b32_e32 v68, 0xffff0000, v20
	v_lshlrev_b32_e32 v66, 16, v20
	v_add_u32_e32 v20, v49, v128
	v_pk_mul_f32 v[56:57], v[56:57], v[60:61] op_sel_hi:[1,0]
	v_pk_mul_f32 v[54:55], v[58:59], v[60:61] op_sel_hi:[1,0]
	v_pk_fma_f32 v[60:61], v[46:47], v[26:27], v[32:33] op_sel_hi:[0,1,1]
	v_pk_fma_f32 v[58:59], v[46:47], v[24:25], v[28:29] op_sel_hi:[0,1,1]
	ds_write_b128 v20, v[42:45] offset:24576
	s_mov_b64 s[98:99], exec
	s_mov_b32 exec_lo, 0xffff0000
	ds_read_b128 v[140:143], v20 offset:24320
	s_mov_b32 exec_lo, 0
	ds_read_b128 v[144:147], v20 offset:24064
	s_mov_b32 exec_hi, 0xffff0000
	ds_read_b128 v[148:151], v20 offset:23808
	s_mov_b64 exec, s[98:99]
	v_mov_b32_e32 v180, 1.0
	s_mov_b32 vcc_lo, 0xffff0000
	s_mov_b32 vcc_hi, -1
	s_waitcnt lgkmcnt(0)
	v_cndmask_b32_e32 v140, 1.0, v140, vcc
	v_cndmask_b32_e32 v141, 1.0, v141, vcc
	v_cndmask_b32_e32 v142, 1.0, v142, vcc
	v_cndmask_b32_e32 v143, 1.0, v143, vcc
	s_mov_b32 vcc_lo, 0
	s_nop 1
	v_cndmask_b32_e32 v144, 1.0, v144, vcc
	v_cndmask_b32_e32 v145, 1.0, v145, vcc
	v_cndmask_b32_e32 v146, 1.0, v146, vcc
	v_cndmask_b32_e32 v147, 1.0, v147, vcc
	s_mov_b32 vcc_hi, 0xffff0000
	s_nop 1
	v_cndmask_b32_e32 v148, 1.0, v148, vcc
	v_cndmask_b32_e32 v149, 1.0, v149, vcc
	v_cndmask_b32_e32 v150, 1.0, v150, vcc
	v_cndmask_b32_e32 v151, 1.0, v151, vcc
	v_pk_mul_f32 v[152:153], v[140:141], v[144:145]
	v_pk_mul_f32 v[154:155], v[142:143], v[146:147]
	v_pk_mul_f32 v[152:153], v[152:153], v[148:149]
	v_pk_mul_f32 v[154:155], v[154:155], v[150:151]
	v_pk_mul_f32 v[156:157], v[152:153], v[42:43]
	v_pk_mul_f32 v[158:159], v[154:155], v[44:45]
	v_rcp_f32_e32 v160, v156
	v_rcp_f32_e32 v161, v157
	v_rcp_f32_e32 v162, v158
	v_rcp_f32_e32 v163, v159
	s_nop 1
	v_cndmask_b32_e32 v160, v160, v180, vcc
	v_cndmask_b32_e32 v161, v161, v180, vcc
	v_cndmask_b32_e32 v162, v162, v180, vcc
	v_cndmask_b32_e32 v163, v163, v180, vcc
	s_mov_b32 exec_lo, 0
	s_mov_b32 exec_hi, 0xffff0000
	ds_write_b128 v20, v[156:159] offset:24576
	s_mov_b64 exec, s[98:99]
	v_pk_mul_f32 v[164:165], v[50:51], v[160:161]
	v_pk_mul_f32 v[166:167], v[52:53], v[162:163]
	ds_write_b128 v20, v[164:167] offset:16384
	v_pk_mul_f32 v[168:169], v[54:55], v[160:161]
	v_pk_mul_f32 v[170:171], v[56:57], v[162:163]
	ds_write_b128 v20, v[168:171] offset:32768
	v_mul_f32_e32 v172, v24, v152
	v_mul_f32_e32 v173, v25, v153
	v_mul_f32_e32 v174, v26, v154
	v_mul_f32_e32 v175, v27, v155
	v_mul_f32_e32 v176, v58, v152
	v_mul_f32_e32 v177, v59, v153
	v_mul_f32_e32 v178, v60, v154
	v_mul_f32_e32 v179, v61, v155
	v_add_u32_e32 v201, 0x2000, v20
	ds_write2_b32 v20, v172, v176 offset1:1
	ds_write2_b32 v20, v173, v177 offset0:2 offset1:3
	ds_write2_b32 v201, v174, v178 offset1:1
	ds_write2_b32 v201, v175, v179 offset0:2 offset1:3
	v_add_u32_e32 v20, v48, v130
	v_mul_f32_e32 v67, v65, v66
	v_mul_f32_e32 v69, v65, v68
	v_mul_f32_e32 v63, v65, v62
	v_mul_f32_e32 v65, v65, v64
	ds_write_b128 v20, v[66:69] offset:40960
	ds_write_b128 v20, v[62:65] offset:40976
	s_and_saveexec_b64 s[2:3], s[0:1]
	s_cbranch_execz .LBB0_195
	v_add_co_u32_e32 v20, vcc, 0x15d01000, v30
	s_nop 1
	v_addc_co_u32_e32 v21, vcc, 0, v31, vcc
	global_store_dword v[20:21], v22, off offset:1024
	s_branch .LBB0_195

.Lrw_scan_loop:
	s_and_b32 s2, s8, 1
	s_mul_i32 s3, s2, 0xe000
	s_lshl_b32 s2, s2, 12
	v_add_u32_e32 v195, s3, v103
	v_add_u32_e32 v33, s3, v38
	v_add_u32_e32 v196, s3, v75
	v_add_u32_e32 v36, s3, v37
	v_add_u32_e32 v102, s2, v76
	ds_read_b128 v[140:143], v195 offset:0
	ds_read_b128 v[152:155], v195 offset:8192
	ds_read_b128 v[176:179], v195 offset:16384
	ds_read_b128 v[84:87], v195 offset:32768
	ds_read_b64 v[4:5], v196 offset:0
	ds_read_b32 v6, v36 offset:0
	ds_read_b128 v[144:147], v195 offset:256
	ds_read_b128 v[156:159], v195 offset:8448
	ds_read_b128 v[180:183], v195 offset:16640
	ds_read_b128 v[88:91], v195 offset:33024
	ds_read_b64 v[8:9], v196 offset:512
	ds_read_b32 v10, v36 offset:512
	s_waitcnt lgkmcnt(6)
	v_pk_mul_f32 v[46:47], v[24:25], v[140:141] op_sel_hi:[0,1]
	v_pk_mul_f32 v[34:35], v[20:21], v[140:141] op_sel_hi:[0,1]
	v_pk_fma_f32 v[46:47], v[24:25], v[142:143], v[46:47] op_sel:[1,0,0] op_sel_hi:[1,1,1]
	v_pk_fma_f32 v[34:35], v[20:21], v[142:143], v[34:35] op_sel:[1,0,0] op_sel_hi:[1,1,1]
	v_pk_fma_f32 v[46:47], v[26:27], v[152:153], v[46:47] op_sel_hi:[0,1,1]
	v_pk_fma_f32 v[34:35], v[22:23], v[152:153], v[34:35] op_sel_hi:[0,1,1]
	v_pk_fma_f32 v[46:47], v[26:27], v[154:155], v[46:47] op_sel:[1,0,0] op_sel_hi:[1,1,1]
	v_pk_fma_f32 v[34:35], v[22:23], v[154:155], v[34:35] op_sel:[1,0,0] op_sel_hi:[1,1,1]
	v_pk_fma_f32 v[20:21], v[176:177], v[4:5], v[20:21] op_sel_hi:[1,0,1]
	v_add_f32_dpp v28, v46, v34 row_half_mirror row_mask:0xf bank_mask:0xf
	v_add_f32_dpp v32, v47, v35 row_half_mirror row_mask:0xf bank_mask:0xf
	v_pk_fma_f32 v[22:23], v[178:179], v[4:5], v[22:23] op_sel_hi:[1,0,1]
	v_add_f32_dpp v28, v28, v28 row_ror:8 row_mask:0xf bank_mask:0xf
	v_add_f32_dpp v32, v32, v32 row_ror:8 row_mask:0xf bank_mask:0xf
	v_pk_fma_f32 v[24:25], v[176:177], v[6:7], v[24:25] op_sel_hi:[1,0,1]
	v_add_f32_dpp v28, v28, v28 quad_perm:[1,0,3,2] row_mask:0xf bank_mask:0xf
	v_add_f32_dpp v32, v32, v32 quad_perm:[1,0,3,2] row_mask:0xf bank_mask:0xf
	v_pk_fma_f32 v[26:27], v[178:179], v[6:7], v[26:27] op_sel_hi:[1,0,1]
	v_add_f32_dpp v28, v28, v28 quad_perm:[2,3,0,1] row_mask:0xf bank_mask:0xf
	v_add_f32_dpp v32, v32, v32 quad_perm:[2,3,0,1] row_mask:0xf bank_mask:0xf
	v_add_f32_e32 v39, v32, v5
	v_mov_b32_dpp v30, v28 row_half_mirror row_mask:0xf bank_mask:0xf
	v_pk_fma_f32 v[20:21], v[84:85], v[28:29], v[20:21] op_sel_hi:[1,0,1] neg_lo:[0,1,0] neg_hi:[0,1,0]
	v_pk_fma_f32 v[22:23], v[86:87], v[28:29], v[22:23] op_sel_hi:[1,0,1] neg_lo:[0,1,0] neg_hi:[0,1,0]
	v_pk_fma_f32 v[24:25], v[84:85], v[30:31], v[24:25] op_sel_hi:[1,0,1] neg_lo:[0,1,0] neg_hi:[0,1,0]
	v_pk_fma_f32 v[26:27], v[86:87], v[30:31], v[26:27] op_sel_hi:[1,0,1] neg_lo:[0,1,0] neg_hi:[0,1,0]
	ds_write_b32 v102, v39 offset:0
	ds_read_b128 v[140:143], v195 offset:512
	ds_read_b128 v[152:155], v195 offset:8704
	ds_read_b128 v[176:179], v195 offset:16896
	ds_read_b128 v[84:87], v195 offset:33280
	ds_read_b64 v[4:5], v196 offset:1024
	ds_read_b32 v6, v36 offset:1024
	s_waitcnt lgkmcnt(7)
	v_pk_mul_f32 v[46:47], v[24:25], v[144:145] op_sel_hi:[0,1]
	v_pk_mul_f32 v[34:35], v[20:21], v[144:145] op_sel_hi:[0,1]
	v_pk_fma_f32 v[46:47], v[24:25], v[146:147], v[46:47] op_sel:[1,0,0] op_sel_hi:[1,1,1]
	v_pk_fma_f32 v[34:35], v[20:21], v[146:147], v[34:35] op_sel:[1,0,0] op_sel_hi:[1,1,1]
	v_pk_fma_f32 v[46:47], v[26:27], v[156:157], v[46:47] op_sel_hi:[0,1,1]
	v_pk_fma_f32 v[34:35], v[22:23], v[156:157], v[34:35] op_sel_hi:[0,1,1]
	v_pk_fma_f32 v[46:47], v[26:27], v[158:159], v[46:47] op_sel:[1,0,0] op_sel_hi:[1,1,1]
	v_pk_fma_f32 v[34:35], v[22:23], v[158:159], v[34:35] op_sel:[1,0,0] op_sel_hi:[1,1,1]
	v_pk_fma_f32 v[20:21], v[180:181], v[8:9], v[20:21] op_sel_hi:[1,0,1]
	v_add_f32_dpp v28, v46, v34 row_half_mirror row_mask:0xf bank_mask:0xf
	v_add_f32_dpp v32, v47, v35 row_half_mirror row_mask:0xf bank_mask:0xf
	v_pk_fma_f32 v[22:23], v[182:183], v[8:9], v[22:23] op_sel_hi:[1,0,1]
	v_add_f32_dpp v28, v28, v28 row_ror:8 row_mask:0xf bank_mask:0xf
	v_add_f32_dpp v32, v32, v32 row_ror:8 row_mask:0xf bank_mask:0xf
	v_pk_fma_f32 v[24:25], v[180:181], v[10:11], v[24:25] op_sel_hi:[1,0,1]
	v_add_f32_dpp v28, v28, v28 quad_perm:[1,0,3,2] row_mask:0xf bank_mask:0xf
	v_add_f32_dpp v32, v32, v32 quad_perm:[1,0,3,2] row_mask:0xf bank_mask:0xf
	v_pk_fma_f32 v[26:27], v[182:183], v[10:11], v[26:27] op_sel_hi:[1,0,1]
	v_add_f32_dpp v28, v28, v28 quad_perm:[2,3,0,1] row_mask:0xf bank_mask:0xf
	v_add_f32_dpp v32, v32, v32 quad_perm:[2,3,0,1] row_mask:0xf bank_mask:0xf
	v_add_f32_e32 v39, v32, v9
	v_mov_b32_dpp v30, v28 row_half_mirror row_mask:0xf bank_mask:0xf
	v_pk_fma_f32 v[20:21], v[88:89], v[28:29], v[20:21] op_sel_hi:[1,0,1] neg_lo:[0,1,0] neg_hi:[0,1,0]
	v_pk_fma_f32 v[22:23], v[90:91], v[28:29], v[22:23] op_sel_hi:[1,0,1] neg_lo:[0,1,0] neg_hi:[0,1,0]
	v_pk_fma_f32 v[24:25], v[88:89], v[30:31], v[24:25] op_sel_hi:[1,0,1] neg_lo:[0,1,0] neg_hi:[0,1,0]
	v_pk_fma_f32 v[26:27], v[90:91], v[30:31], v[26:27] op_sel_hi:[1,0,1] neg_lo:[0,1,0] neg_hi:[0,1,0]
	ds_write_b32 v102, v39 offset:128
	ds_read_b128 v[144:147], v195 offset:768
	ds_read_b128 v[156:159], v195 offset:8960
	ds_read_b128 v[168:171], v195 offset:25344
	ds_read_b128 v[180:183], v195 offset:17152
	ds_read_b128 v[88:91], v195 offset:33536
	ds_read_b64 v[8:9], v196 offset:1536
	ds_read_b32 v10, v36 offset:1536
	s_waitcnt lgkmcnt(8)
	v_pk_mul_f32 v[46:47], v[24:25], v[140:141] op_sel_hi:[0,1]
	v_pk_mul_f32 v[34:35], v[20:21], v[140:141] op_sel_hi:[0,1]
	v_pk_fma_f32 v[46:47], v[24:25], v[142:143], v[46:47] op_sel:[1,0,0] op_sel_hi:[1,1,1]
	v_pk_fma_f32 v[34:35], v[20:21], v[142:143], v[34:35] op_sel:[1,0,0] op_sel_hi:[1,1,1]
	v_pk_fma_f32 v[46:47], v[26:27], v[152:153], v[46:47] op_sel_hi:[0,1,1]
	v_pk_fma_f32 v[34:35], v[22:23], v[152:153], v[34:35] op_sel_hi:[0,1,1]
	v_pk_fma_f32 v[46:47], v[26:27], v[154:155], v[46:47] op_sel:[1,0,0] op_sel_hi:[1,1,1]
	v_pk_fma_f32 v[34:35], v[22:23], v[154:155], v[34:35] op_sel:[1,0,0] op_sel_hi:[1,1,1]
	v_pk_fma_f32 v[20:21], v[176:177], v[4:5], v[20:21] op_sel_hi:[1,0,1]
	v_add_f32_dpp v28, v46, v34 row_half_mirror row_mask:0xf bank_mask:0xf
	v_add_f32_dpp v32, v47, v35 row_half_mirror row_mask:0xf bank_mask:0xf
	v_pk_fma_f32 v[22:23], v[178:179], v[4:5], v[22:23] op_sel_hi:[1,0,1]
	v_add_f32_dpp v28, v28, v28 row_ror:8 row_mask:0xf bank_mask:0xf
	v_add_f32_dpp v32, v32, v32 row_ror:8 row_mask:0xf bank_mask:0xf
	v_pk_fma_f32 v[24:25], v[176:177], v[6:7], v[24:25] op_sel_hi:[1,0,1]
	v_add_f32_dpp v28, v28, v28 quad_perm:[1,0,3,2] row_mask:0xf bank_mask:0xf
	v_add_f32_dpp v32, v32, v32 quad_perm:[1,0,3,2] row_mask:0xf bank_mask:0xf
	v_pk_fma_f32 v[26:27], v[178:179], v[6:7], v[26:27] op_sel_hi:[1,0,1]
	v_add_f32_dpp v28, v28, v28 quad_perm:[2,3,0,1] row_mask:0xf bank_mask:0xf
	v_add_f32_dpp v32, v32, v32 quad_perm:[2,3,0,1] row_mask:0xf bank_mask:0xf
	v_add_f32_e32 v39, v32, v5
	v_mov_b32_dpp v30, v28 row_half_mirror row_mask:0xf bank_mask:0xf
	v_pk_fma_f32 v[20:21], v[84:85], v[28:29], v[20:21] op_sel_hi:[1,0,1] neg_lo:[0,1,0] neg_hi:[0,1,0]
	v_pk_fma_f32 v[22:23], v[86:87], v[28:29], v[22:23] op_sel_hi:[1,0,1] neg_lo:[0,1,0] neg_hi:[0,1,0]
	v_pk_fma_f32 v[24:25], v[84:85], v[30:31], v[24:25] op_sel_hi:[1,0,1] neg_lo:[0,1,0] neg_hi:[0,1,0]
	v_pk_fma_f32 v[26:27], v[86:87], v[30:31], v[26:27] op_sel_hi:[1,0,1] neg_lo:[0,1,0] neg_hi:[0,1,0]
	ds_write_b32 v102, v39 offset:256
	ds_read_b128 v[140:143], v195 offset:1024
	ds_read_b128 v[152:155], v195 offset:9216
	ds_read_b128 v[176:179], v195 offset:17408
	ds_read_b128 v[84:87], v195 offset:33792
	ds_read_b64 v[4:5], v196 offset:2048
	ds_read_b32 v6, v36 offset:2048
	s_waitcnt lgkmcnt(7)
	v_pk_mul_f32 v[46:47], v[24:25], v[144:145] op_sel_hi:[0,1]
	v_pk_mul_f32 v[34:35], v[20:21], v[144:145] op_sel_hi:[0,1]
	v_pk_fma_f32 v[46:47], v[24:25], v[146:147], v[46:47] op_sel:[1,0,0] op_sel_hi:[1,1,1]
	v_pk_fma_f32 v[34:35], v[20:21], v[146:147], v[34:35] op_sel:[1,0,0] op_sel_hi:[1,1,1]
	v_pk_fma_f32 v[46:47], v[26:27], v[156:157], v[46:47] op_sel_hi:[0,1,1]
	v_pk_fma_f32 v[34:35], v[22:23], v[156:157], v[34:35] op_sel_hi:[0,1,1]
	v_pk_fma_f32 v[46:47], v[26:27], v[158:159], v[46:47] op_sel:[1,0,0] op_sel_hi:[1,1,1]
	v_pk_fma_f32 v[34:35], v[22:23], v[158:159], v[34:35] op_sel:[1,0,0] op_sel_hi:[1,1,1]
	v_pk_mul_f32 v[20:21], v[20:21], v[168:169]
	v_add_f32_dpp v28, v46, v34 row_half_mirror row_mask:0xf bank_mask:0xf
	v_add_f32_dpp v32, v47, v35 row_half_mirror row_mask:0xf bank_mask:0xf
	v_pk_mul_f32 v[22:23], v[22:23], v[170:171]
	v_add_f32_dpp v28, v28, v28 row_ror:8 row_mask:0xf bank_mask:0xf
	v_add_f32_dpp v32, v32, v32 row_ror:8 row_mask:0xf bank_mask:0xf
	v_pk_mul_f32 v[24:25], v[24:25], v[168:169]
	v_add_f32_dpp v28, v28, v28 quad_perm:[1,0,3,2] row_mask:0xf bank_mask:0xf
	v_add_f32_dpp v32, v32, v32 quad_perm:[1,0,3,2] row_mask:0xf bank_mask:0xf
	v_pk_mul_f32 v[26:27], v[26:27], v[170:171]
	v_add_f32_dpp v28, v28, v28 quad_perm:[2,3,0,1] row_mask:0xf bank_mask:0xf
	v_add_f32_dpp v32, v32, v32 quad_perm:[2,3,0,1] row_mask:0xf bank_mask:0xf
	v_pk_fma_f32 v[20:21], v[180:181], v[8:9], v[20:21] op_sel_hi:[1,0,1]
	v_mov_b32_dpp v30, v28 row_half_mirror row_mask:0xf bank_mask:0xf
	v_pk_fma_f32 v[22:23], v[182:183], v[8:9], v[22:23] op_sel_hi:[1,0,1]
	v_pk_fma_f32 v[24:25], v[180:181], v[10:11], v[24:25] op_sel_hi:[1,0,1]
	v_pk_fma_f32 v[26:27], v[182:183], v[10:11], v[26:27] op_sel_hi:[1,0,1]
	v_pk_fma_f32 v[20:21], v[88:89], v[28:29], v[20:21] op_sel_hi:[1,0,1] neg_lo:[0,1,0] neg_hi:[0,1,0]
	v_pk_fma_f32 v[22:23], v[90:91], v[28:29], v[22:23] op_sel_hi:[1,0,1] neg_lo:[0,1,0] neg_hi:[0,1,0]
	v_pk_fma_f32 v[24:25], v[88:89], v[30:31], v[24:25] op_sel_hi:[1,0,1] neg_lo:[0,1,0] neg_hi:[0,1,0]
	v_pk_fma_f32 v[26:27], v[90:91], v[30:31], v[26:27] op_sel_hi:[1,0,1] neg_lo:[0,1,0] neg_hi:[0,1,0]
	v_add_f32_e32 v39, v32, v9
	ds_write_b32 v102, v39 offset:384
	ds_read_b128 v[144:147], v195 offset:1280
	ds_read_b128 v[156:159], v195 offset:9472
	ds_read_b128 v[180:183], v195 offset:17664
	ds_read_b128 v[88:91], v195 offset:34048
	ds_read_b64 v[8:9], v196 offset:2560
	ds_read_b32 v10, v36 offset:2560
	s_waitcnt lgkmcnt(7)
	v_pk_mul_f32 v[46:47], v[24:25], v[140:141] op_sel_hi:[0,1]
	v_pk_mul_f32 v[34:35], v[20:21], v[140:141] op_sel_hi:[0,1]
	v_pk_fma_f32 v[46:47], v[24:25], v[142:143], v[46:47] op_sel:[1,0,0] op_sel_hi:[1,1,1]
	v_pk_fma_f32 v[34:35], v[20:21], v[142:143], v[34:35] op_sel:[1,0,0] op_sel_hi:[1,1,1]
	v_pk_fma_f32 v[46:47], v[26:27], v[152:153], v[46:47] op_sel_hi:[0,1,1]
	v_pk_fma_f32 v[34:35], v[22:23], v[152:153], v[34:35] op_sel_hi:[0,1,1]
	v_pk_fma_f32 v[46:47], v[26:27], v[154:155], v[46:47] op_sel:[1,0,0] op_sel_hi:[1,1,1]
	v_pk_fma_f32 v[34:35], v[22:23], v[154:155], v[34:35] op_sel:[1,0,0] op_sel_hi:[1,1,1]
	v_pk_fma_f32 v[20:21], v[176:177], v[4:5], v[20:21] op_sel_hi:[1,0,1]
	v_add_f32_dpp v28, v46, v34 row_half_mirror row_mask:0xf bank_mask:0xf
	v_add_f32_dpp v32, v47, v35 row_half_mirror row_mask:0xf bank_mask:0xf
	v_pk_fma_f32 v[22:23], v[178:179], v[4:5], v[22:23] op_sel_hi:[1,0,1]
	v_add_f32_dpp v28, v28, v28 row_ror:8 row_mask:0xf bank_mask:0xf
	v_add_f32_dpp v32, v32, v32 row_ror:8 row_mask:0xf bank_mask:0xf
	v_pk_fma_f32 v[24:25], v[176:177], v[6:7], v[24:25] op_sel_hi:[1,0,1]
	v_add_f32_dpp v28, v28, v28 quad_perm:[1,0,3,2] row_mask:0xf bank_mask:0xf
	v_add_f32_dpp v32, v32, v32 quad_perm:[1,0,3,2] row_mask:0xf bank_mask:0xf
	v_pk_fma_f32 v[26:27], v[178:179], v[6:7], v[26:27] op_sel_hi:[1,0,1]
	v_add_f32_dpp v28, v28, v28 quad_perm:[2,3,0,1] row_mask:0xf bank_mask:0xf
	v_add_f32_dpp v32, v32, v32 quad_perm:[2,3,0,1] row_mask:0xf bank_mask:0xf
	v_add_f32_e32 v39, v32, v5
	v_mov_b32_dpp v30, v28 row_half_mirror row_mask:0xf bank_mask:0xf
	v_pk_fma_f32 v[20:21], v[84:85], v[28:29], v[20:21] op_sel_hi:[1,0,1] neg_lo:[0,1,0] neg_hi:[0,1,0]
	v_pk_fma_f32 v[22:23], v[86:87], v[28:29], v[22:23] op_sel_hi:[1,0,1] neg_lo:[0,1,0] neg_hi:[0,1,0]
	v_pk_fma_f32 v[24:25], v[84:85], v[30:31], v[24:25] op_sel_hi:[1,0,1] neg_lo:[0,1,0] neg_hi:[0,1,0]
	v_pk_fma_f32 v[26:27], v[86:87], v[30:31], v[26:27] op_sel_hi:[1,0,1] neg_lo:[0,1,0] neg_hi:[0,1,0]
	ds_write_b32 v102, v39 offset:512
	ds_read_b128 v[140:143], v195 offset:1536
	ds_read_b128 v[152:155], v195 offset:9728
	ds_read_b128 v[176:179], v195 offset:17920
	ds_read_b128 v[84:87], v195 offset:34304
	ds_read_b64 v[4:5], v196 offset:3072
	ds_read_b32 v6, v36 offset:3072
	s_waitcnt lgkmcnt(7)
	v_pk_mul_f32 v[46:47], v[24:25], v[144:145] op_sel_hi:[0,1]
	v_pk_mul_f32 v[34:35], v[20:21], v[144:145] op_sel_hi:[0,1]
	v_pk_fma_f32 v[46:47], v[24:25], v[146:147], v[46:47] op_sel:[1,0,0] op_sel_hi:[1,1,1]
	v_pk_fma_f32 v[34:35], v[20:21], v[146:147], v[34:35] op_sel:[1,0,0] op_sel_hi:[1,1,1]
	v_pk_fma_f32 v[46:47], v[26:27], v[156:157], v[46:47] op_sel_hi:[0,1,1]
	v_pk_fma_f32 v[34:35], v[22:23], v[156:157], v[34:35] op_sel_hi:[0,1,1]
	v_pk_fma_f32 v[46:47], v[26:27], v[158:159], v[46:47] op_sel:[1,0,0] op_sel_hi:[1,1,1]
	v_pk_fma_f32 v[34:35], v[22:23], v[158:159], v[34:35] op_sel:[1,0,0] op_sel_hi:[1,1,1]
	v_pk_fma_f32 v[20:21], v[180:181], v[8:9], v[20:21] op_sel_hi:[1,0,1]
	v_add_f32_dpp v28, v46, v34 row_half_mirror row_mask:0xf bank_mask:0xf
	v_add_f32_dpp v32, v47, v35 row_half_mirror row_mask:0xf bank_mask:0xf
	v_pk_fma_f32 v[22:23], v[182:183], v[8:9], v[22:23] op_sel_hi:[1,0,1]
	v_add_f32_dpp v28, v28, v28 row_ror:8 row_mask:0xf bank_mask:0xf
	v_add_f32_dpp v32, v32, v32 row_ror:8 row_mask:0xf bank_mask:0xf
	v_pk_fma_f32 v[24:25], v[180:181], v[10:11], v[24:25] op_sel_hi:[1,0,1]
	v_add_f32_dpp v28, v28, v28 quad_perm:[1,0,3,2] row_mask:0xf bank_mask:0xf
	v_add_f32_dpp v32, v32, v32 quad_perm:[1,0,3,2] row_mask:0xf bank_mask:0xf
	v_pk_fma_f32 v[26:27], v[182:183], v[10:11], v[26:27] op_sel_hi:[1,0,1]
	v_add_f32_dpp v28, v28, v28 quad_perm:[2,3,0,1] row_mask:0xf bank_mask:0xf
	v_add_f32_dpp v32, v32, v32 quad_perm:[2,3,0,1] row_mask:0xf bank_mask:0xf
	v_add_f32_e32 v39, v32, v9
	v_mov_b32_dpp v30, v28 row_half_mirror row_mask:0xf bank_mask:0xf
	v_pk_fma_f32 v[20:21], v[88:89], v[28:29], v[20:21] op_sel_hi:[1,0,1] neg_lo:[0,1,0] neg_hi:[0,1,0]
	v_pk_fma_f32 v[22:23], v[90:91], v[28:29], v[22:23] op_sel_hi:[1,0,1] neg_lo:[0,1,0] neg_hi:[0,1,0]
	v_pk_fma_f32 v[24:25], v[88:89], v[30:31], v[24:25] op_sel_hi:[1,0,1] neg_lo:[0,1,0] neg_hi:[0,1,0]
	v_pk_fma_f32 v[26:27], v[90:91], v[30:31], v[26:27] op_sel_hi:[1,0,1] neg_lo:[0,1,0] neg_hi:[0,1,0]
	ds_write_b32 v102, v39 offset:640
	ds_read_b128 v[144:147], v195 offset:1792
	ds_read_b128 v[156:159], v195 offset:9984
	ds_read_b128 v[168:171], v195 offset:26368
	ds_read_b128 v[180:183], v195 offset:18176
	ds_read_b128 v[88:91], v195 offset:34560
	ds_read_b64 v[8:9], v196 offset:3584
	ds_read_b32 v10, v36 offset:3584
	s_waitcnt lgkmcnt(8)
	v_pk_mul_f32 v[46:47], v[24:25], v[140:141] op_sel_hi:[0,1]
	v_pk_mul_f32 v[34:35], v[20:21], v[140:141] op_sel_hi:[0,1]
	v_pk_fma_f32 v[46:47], v[24:25], v[142:143], v[46:47] op_sel:[1,0,0] op_sel_hi:[1,1,1]
	v_pk_fma_f32 v[34:35], v[20:21], v[142:143], v[34:35] op_sel:[1,0,0] op_sel_hi:[1,1,1]
	v_pk_fma_f32 v[46:47], v[26:27], v[152:153], v[46:47] op_sel_hi:[0,1,1]
	v_pk_fma_f32 v[34:35], v[22:23], v[152:153], v[34:35] op_sel_hi:[0,1,1]
	v_pk_fma_f32 v[46:47], v[26:27], v[154:155], v[46:47] op_sel:[1,0,0] op_sel_hi:[1,1,1]
	v_pk_fma_f32 v[34:35], v[22:23], v[154:155], v[34:35] op_sel:[1,0,0] op_sel_hi:[1,1,1]
	v_pk_fma_f32 v[20:21], v[176:177], v[4:5], v[20:21] op_sel_hi:[1,0,1]
	v_add_f32_dpp v28, v46, v34 row_half_mirror row_mask:0xf bank_mask:0xf
	v_add_f32_dpp v32, v47, v35 row_half_mirror row_mask:0xf bank_mask:0xf
	v_pk_fma_f32 v[22:23], v[178:179], v[4:5], v[22:23] op_sel_hi:[1,0,1]
	v_add_f32_dpp v28, v28, v28 row_ror:8 row_mask:0xf bank_mask:0xf
	v_add_f32_dpp v32, v32, v32 row_ror:8 row_mask:0xf bank_mask:0xf
	v_pk_fma_f32 v[24:25], v[176:177], v[6:7], v[24:25] op_sel_hi:[1,0,1]
	v_add_f32_dpp v28, v28, v28 quad_perm:[1,0,3,2] row_mask:0xf bank_mask:0xf
	v_add_f32_dpp v32, v32, v32 quad_perm:[1,0,3,2] row_mask:0xf bank_mask:0xf
	v_pk_fma_f32 v[26:27], v[178:179], v[6:7], v[26:27] op_sel_hi:[1,0,1]
	v_add_f32_dpp v28, v28, v28 quad_perm:[2,3,0,1] row_mask:0xf bank_mask:0xf
	v_add_f32_dpp v32, v32, v32 quad_perm:[2,3,0,1] row_mask:0xf bank_mask:0xf
	v_add_f32_e32 v39, v32, v5
	v_mov_b32_dpp v30, v28 row_half_mirror row_mask:0xf bank_mask:0xf
	v_pk_fma_f32 v[20:21], v[84:85], v[28:29], v[20:21] op_sel_hi:[1,0,1] neg_lo:[0,1,0] neg_hi:[0,1,0]
	v_pk_fma_f32 v[22:23], v[86:87], v[28:29], v[22:23] op_sel_hi:[1,0,1] neg_lo:[0,1,0] neg_hi:[0,1,0]
	v_pk_fma_f32 v[24:25], v[84:85], v[30:31], v[24:25] op_sel_hi:[1,0,1] neg_lo:[0,1,0] neg_hi:[0,1,0]
	v_pk_fma_f32 v[26:27], v[86:87], v[30:31], v[26:27] op_sel_hi:[1,0,1] neg_lo:[0,1,0] neg_hi:[0,1,0]
	ds_write_b32 v102, v39 offset:768
	ds_read_b128 v[140:143], v195 offset:2048
	ds_read_b128 v[152:155], v195 offset:10240
	ds_read_b128 v[176:179], v195 offset:18432
	ds_read_b128 v[84:87], v195 offset:34816
	ds_read_b64 v[4:5], v196 offset:4096
	ds_read_b32 v6, v36 offset:4096
	s_waitcnt lgkmcnt(7)
	v_pk_mul_f32 v[46:47], v[24:25], v[144:145] op_sel_hi:[0,1]
	v_pk_mul_f32 v[34:35], v[20:21], v[144:145] op_sel_hi:[0,1]
	v_pk_fma_f32 v[46:47], v[24:25], v[146:147], v[46:47] op_sel:[1,0,0] op_sel_hi:[1,1,1]
	v_pk_fma_f32 v[34:35], v[20:21], v[146:147], v[34:35] op_sel:[1,0,0] op_sel_hi:[1,1,1]
	v_pk_fma_f32 v[46:47], v[26:27], v[156:157], v[46:47] op_sel_hi:[0,1,1]
	v_pk_fma_f32 v[34:35], v[22:23], v[156:157], v[34:35] op_sel_hi:[0,1,1]
	v_pk_fma_f32 v[46:47], v[26:27], v[158:159], v[46:47] op_sel:[1,0,0] op_sel_hi:[1,1,1]
	v_pk_fma_f32 v[34:35], v[22:23], v[158:159], v[34:35] op_sel:[1,0,0] op_sel_hi:[1,1,1]
	v_pk_mul_f32 v[20:21], v[20:21], v[168:169]
	v_add_f32_dpp v28, v46, v34 row_half_mirror row_mask:0xf bank_mask:0xf
	v_add_f32_dpp v32, v47, v35 row_half_mirror row_mask:0xf bank_mask:0xf
	v_pk_mul_f32 v[22:23], v[22:23], v[170:171]
	v_add_f32_dpp v28, v28, v28 row_ror:8 row_mask:0xf bank_mask:0xf
	v_add_f32_dpp v32, v32, v32 row_ror:8 row_mask:0xf bank_mask:0xf
	v_pk_mul_f32 v[24:25], v[24:25], v[168:169]
	v_add_f32_dpp v28, v28, v28 quad_perm:[1,0,3,2] row_mask:0xf bank_mask:0xf
	v_add_f32_dpp v32, v32, v32 quad_perm:[1,0,3,2] row_mask:0xf bank_mask:0xf
	v_pk_mul_f32 v[26:27], v[26:27], v[170:171]
	v_add_f32_dpp v28, v28, v28 quad_perm:[2,3,0,1] row_mask:0xf bank_mask:0xf
	v_add_f32_dpp v32, v32, v32 quad_perm:[2,3,0,1] row_mask:0xf bank_mask:0xf
	v_pk_fma_f32 v[20:21], v[180:181], v[8:9], v[20:21] op_sel_hi:[1,0,1]
	v_mov_b32_dpp v30, v28 row_half_mirror row_mask:0xf bank_mask:0xf
	v_pk_fma_f32 v[22:23], v[182:183], v[8:9], v[22:23] op_sel_hi:[1,0,1]
	v_pk_fma_f32 v[24:25], v[180:181], v[10:11], v[24:25] op_sel_hi:[1,0,1]
	v_pk_fma_f32 v[26:27], v[182:183], v[10:11], v[26:27] op_sel_hi:[1,0,1]
	v_pk_fma_f32 v[20:21], v[88:89], v[28:29], v[20:21] op_sel_hi:[1,0,1] neg_lo:[0,1,0] neg_hi:[0,1,0]
	v_pk_fma_f32 v[22:23], v[90:91], v[28:29], v[22:23] op_sel_hi:[1,0,1] neg_lo:[0,1,0] neg_hi:[0,1,0]
	v_pk_fma_f32 v[24:25], v[88:89], v[30:31], v[24:25] op_sel_hi:[1,0,1] neg_lo:[0,1,0] neg_hi:[0,1,0]
	v_pk_fma_f32 v[26:27], v[90:91], v[30:31], v[26:27] op_sel_hi:[1,0,1] neg_lo:[0,1,0] neg_hi:[0,1,0]
	v_add_f32_e32 v39, v32, v9
	ds_write_b32 v102, v39 offset:896
	ds_read_b128 v[144:147], v195 offset:2304
	ds_read_b128 v[156:159], v195 offset:10496
	ds_read_b128 v[180:183], v195 offset:18688
	ds_read_b128 v[88:91], v195 offset:35072
	ds_read_b64 v[8:9], v196 offset:4608
	ds_read_b32 v10, v36 offset:4608
	s_waitcnt lgkmcnt(7)
	v_pk_mul_f32 v[46:47], v[24:25], v[140:141] op_sel_hi:[0,1]
	v_pk_mul_f32 v[34:35], v[20:21], v[140:141] op_sel_hi:[0,1]
	v_pk_fma_f32 v[46:47], v[24:25], v[142:143], v[46:47] op_sel:[1,0,0] op_sel_hi:[1,1,1]
	v_pk_fma_f32 v[34:35], v[20:21], v[142:143], v[34:35] op_sel:[1,0,0] op_sel_hi:[1,1,1]
	v_pk_fma_f32 v[46:47], v[26:27], v[152:153], v[46:47] op_sel_hi:[0,1,1]
	v_pk_fma_f32 v[34:35], v[22:23], v[152:153], v[34:35] op_sel_hi:[0,1,1]
	v_pk_fma_f32 v[46:47], v[26:27], v[154:155], v[46:47] op_sel:[1,0,0] op_sel_hi:[1,1,1]
	v_pk_fma_f32 v[34:35], v[22:23], v[154:155], v[34:35] op_sel:[1,0,0] op_sel_hi:[1,1,1]
	v_pk_fma_f32 v[20:21], v[176:177], v[4:5], v[20:21] op_sel_hi:[1,0,1]
	v_add_f32_dpp v28, v46, v34 row_half_mirror row_mask:0xf bank_mask:0xf
	v_add_f32_dpp v32, v47, v35 row_half_mirror row_mask:0xf bank_mask:0xf
	v_pk_fma_f32 v[22:23], v[178:179], v[4:5], v[22:23] op_sel_hi:[1,0,1]
	v_add_f32_dpp v28, v28, v28 row_ror:8 row_mask:0xf bank_mask:0xf
	v_add_f32_dpp v32, v32, v32 row_ror:8 row_mask:0xf bank_mask:0xf
	v_pk_fma_f32 v[24:25], v[176:177], v[6:7], v[24:25] op_sel_hi:[1,0,1]
	v_add_f32_dpp v28, v28, v28 quad_perm:[1,0,3,2] row_mask:0xf bank_mask:0xf
	v_add_f32_dpp v32, v32, v32 quad_perm:[1,0,3,2] row_mask:0xf bank_mask:0xf
	v_pk_fma_f32 v[26:27], v[178:179], v[6:7], v[26:27] op_sel_hi:[1,0,1]
	v_add_f32_dpp v28, v28, v28 quad_perm:[2,3,0,1] row_mask:0xf bank_mask:0xf
	v_add_f32_dpp v32, v32, v32 quad_perm:[2,3,0,1] row_mask:0xf bank_mask:0xf
	v_add_f32_e32 v39, v32, v5
	v_mov_b32_dpp v30, v28 row_half_mirror row_mask:0xf bank_mask:0xf
	v_pk_fma_f32 v[20:21], v[84:85], v[28:29], v[20:21] op_sel_hi:[1,0,1] neg_lo:[0,1,0] neg_hi:[0,1,0]
	v_pk_fma_f32 v[22:23], v[86:87], v[28:29], v[22:23] op_sel_hi:[1,0,1] neg_lo:[0,1,0] neg_hi:[0,1,0]
	v_pk_fma_f32 v[24:25], v[84:85], v[30:31], v[24:25] op_sel_hi:[1,0,1] neg_lo:[0,1,0] neg_hi:[0,1,0]
	v_pk_fma_f32 v[26:27], v[86:87], v[30:31], v[26:27] op_sel_hi:[1,0,1] neg_lo:[0,1,0] neg_hi:[0,1,0]
	ds_write_b32 v102, v39 offset:1024
	ds_read_b128 v[140:143], v195 offset:2560
	ds_read_b128 v[152:155], v195 offset:10752
	ds_read_b128 v[176:179], v195 offset:18944
	ds_read_b128 v[84:87], v195 offset:35328
	ds_read_b64 v[4:5], v196 offset:5120
	ds_read_b32 v6, v36 offset:5120
	s_waitcnt lgkmcnt(7)
	v_pk_mul_f32 v[46:47], v[24:25], v[144:145] op_sel_hi:[0,1]
	v_pk_mul_f32 v[34:35], v[20:21], v[144:145] op_sel_hi:[0,1]
	v_pk_fma_f32 v[46:47], v[24:25], v[146:147], v[46:47] op_sel:[1,0,0] op_sel_hi:[1,1,1]
	v_pk_fma_f32 v[34:35], v[20:21], v[146:147], v[34:35] op_sel:[1,0,0] op_sel_hi:[1,1,1]
	v_pk_fma_f32 v[46:47], v[26:27], v[156:157], v[46:47] op_sel_hi:[0,1,1]
	v_pk_fma_f32 v[34:35], v[22:23], v[156:157], v[34:35] op_sel_hi:[0,1,1]
	v_pk_fma_f32 v[46:47], v[26:27], v[158:159], v[46:47] op_sel:[1,0,0] op_sel_hi:[1,1,1]
	v_pk_fma_f32 v[34:35], v[22:23], v[158:159], v[34:35] op_sel:[1,0,0] op_sel_hi:[1,1,1]
	v_pk_fma_f32 v[20:21], v[180:181], v[8:9], v[20:21] op_sel_hi:[1,0,1]
	v_add_f32_dpp v28, v46, v34 row_half_mirror row_mask:0xf bank_mask:0xf
	v_add_f32_dpp v32, v47, v35 row_half_mirror row_mask:0xf bank_mask:0xf
	v_pk_fma_f32 v[22:23], v[182:183], v[8:9], v[22:23] op_sel_hi:[1,0,1]
	v_add_f32_dpp v28, v28, v28 row_ror:8 row_mask:0xf bank_mask:0xf
	v_add_f32_dpp v32, v32, v32 row_ror:8 row_mask:0xf bank_mask:0xf
	v_pk_fma_f32 v[24:25], v[180:181], v[10:11], v[24:25] op_sel_hi:[1,0,1]
	v_add_f32_dpp v28, v28, v28 quad_perm:[1,0,3,2] row_mask:0xf bank_mask:0xf
	v_add_f32_dpp v32, v32, v32 quad_perm:[1,0,3,2] row_mask:0xf bank_mask:0xf
	v_pk_fma_f32 v[26:27], v[182:183], v[10:11], v[26:27] op_sel_hi:[1,0,1]
	v_add_f32_dpp v28, v28, v28 quad_perm:[2,3,0,1] row_mask:0xf bank_mask:0xf
	v_add_f32_dpp v32, v32, v32 quad_perm:[2,3,0,1] row_mask:0xf bank_mask:0xf
	v_add_f32_e32 v39, v32, v9
	v_mov_b32_dpp v30, v28 row_half_mirror row_mask:0xf bank_mask:0xf
	v_pk_fma_f32 v[20:21], v[88:89], v[28:29], v[20:21] op_sel_hi:[1,0,1] neg_lo:[0,1,0] neg_hi:[0,1,0]
	v_pk_fma_f32 v[22:23], v[90:91], v[28:29], v[22:23] op_sel_hi:[1,0,1] neg_lo:[0,1,0] neg_hi:[0,1,0]
	v_pk_fma_f32 v[24:25], v[88:89], v[30:31], v[24:25] op_sel_hi:[1,0,1] neg_lo:[0,1,0] neg_hi:[0,1,0]
	v_pk_fma_f32 v[26:27], v[90:91], v[30:31], v[26:27] op_sel_hi:[1,0,1] neg_lo:[0,1,0] neg_hi:[0,1,0]
	ds_write_b32 v102, v39 offset:1152
	ds_read_b128 v[144:147], v195 offset:2816
	ds_read_b128 v[156:159], v195 offset:11008
	ds_read_b128 v[168:171], v195 offset:27392
	ds_read_b128 v[180:183], v195 offset:19200
	ds_read_b128 v[88:91], v195 offset:35584
	ds_read_b64 v[8:9], v196 offset:5632
	ds_read_b32 v10, v36 offset:5632
	s_waitcnt lgkmcnt(8)
	v_pk_mul_f32 v[46:47], v[24:25], v[140:141] op_sel_hi:[0,1]
	v_pk_mul_f32 v[34:35], v[20:21], v[140:141] op_sel_hi:[0,1]
	v_pk_fma_f32 v[46:47], v[24:25], v[142:143], v[46:47] op_sel:[1,0,0] op_sel_hi:[1,1,1]
	v_pk_fma_f32 v[34:35], v[20:21], v[142:143], v[34:35] op_sel:[1,0,0] op_sel_hi:[1,1,1]
	v_pk_fma_f32 v[46:47], v[26:27], v[152:153], v[46:47] op_sel_hi:[0,1,1]
	v_pk_fma_f32 v[34:35], v[22:23], v[152:153], v[34:35] op_sel_hi:[0,1,1]
	v_pk_fma_f32 v[46:47], v[26:27], v[154:155], v[46:47] op_sel:[1,0,0] op_sel_hi:[1,1,1]
	v_pk_fma_f32 v[34:35], v[22:23], v[154:155], v[34:35] op_sel:[1,0,0] op_sel_hi:[1,1,1]
	v_pk_fma_f32 v[20:21], v[176:177], v[4:5], v[20:21] op_sel_hi:[1,0,1]
	v_add_f32_dpp v28, v46, v34 row_half_mirror row_mask:0xf bank_mask:0xf
	v_add_f32_dpp v32, v47, v35 row_half_mirror row_mask:0xf bank_mask:0xf
	v_pk_fma_f32 v[22:23], v[178:179], v[4:5], v[22:23] op_sel_hi:[1,0,1]
	v_add_f32_dpp v28, v28, v28 row_ror:8 row_mask:0xf bank_mask:0xf
	v_add_f32_dpp v32, v32, v32 row_ror:8 row_mask:0xf bank_mask:0xf
	v_pk_fma_f32 v[24:25], v[176:177], v[6:7], v[24:25] op_sel_hi:[1,0,1]
	v_add_f32_dpp v28, v28, v28 quad_perm:[1,0,3,2] row_mask:0xf bank_mask:0xf
	v_add_f32_dpp v32, v32, v32 quad_perm:[1,0,3,2] row_mask:0xf bank_mask:0xf
	v_pk_fma_f32 v[26:27], v[178:179], v[6:7], v[26:27] op_sel_hi:[1,0,1]
	v_add_f32_dpp v28, v28, v28 quad_perm:[2,3,0,1] row_mask:0xf bank_mask:0xf
	v_add_f32_dpp v32, v32, v32 quad_perm:[2,3,0,1] row_mask:0xf bank_mask:0xf
	v_add_f32_e32 v39, v32, v5
	v_mov_b32_dpp v30, v28 row_half_mirror row_mask:0xf bank_mask:0xf
	v_pk_fma_f32 v[20:21], v[84:85], v[28:29], v[20:21] op_sel_hi:[1,0,1] neg_lo:[0,1,0] neg_hi:[0,1,0]
	v_pk_fma_f32 v[22:23], v[86:87], v[28:29], v[22:23] op_sel_hi:[1,0,1] neg_lo:[0,1,0] neg_hi:[0,1,0]
	v_pk_fma_f32 v[24:25], v[84:85], v[30:31], v[24:25] op_sel_hi:[1,0,1] neg_lo:[0,1,0] neg_hi:[0,1,0]
	v_pk_fma_f32 v[26:27], v[86:87], v[30:31], v[26:27] op_sel_hi:[1,0,1] neg_lo:[0,1,0] neg_hi:[0,1,0]
	ds_write_b32 v102, v39 offset:1280
	ds_read_b128 v[140:143], v195 offset:3072
	ds_read_b128 v[152:155], v195 offset:11264
	ds_read_b128 v[176:179], v195 offset:19456
	ds_read_b128 v[84:87], v195 offset:35840
	ds_read_b64 v[4:5], v196 offset:6144
	ds_read_b32 v6, v36 offset:6144
	s_waitcnt lgkmcnt(7)
	v_pk_mul_f32 v[46:47], v[24:25], v[144:145] op_sel_hi:[0,1]
	v_pk_mul_f32 v[34:35], v[20:21], v[144:145] op_sel_hi:[0,1]
	v_pk_fma_f32 v[46:47], v[24:25], v[146:147], v[46:47] op_sel:[1,0,0] op_sel_hi:[1,1,1]
	v_pk_fma_f32 v[34:35], v[20:21], v[146:147], v[34:35] op_sel:[1,0,0] op_sel_hi:[1,1,1]
	v_pk_fma_f32 v[46:47], v[26:27], v[156:157], v[46:47] op_sel_hi:[0,1,1]
	v_pk_fma_f32 v[34:35], v[22:23], v[156:157], v[34:35] op_sel_hi:[0,1,1]
	v_pk_fma_f32 v[46:47], v[26:27], v[158:159], v[46:47] op_sel:[1,0,0] op_sel_hi:[1,1,1]
	v_pk_fma_f32 v[34:35], v[22:23], v[158:159], v[34:35] op_sel:[1,0,0] op_sel_hi:[1,1,1]
	v_pk_mul_f32 v[20:21], v[20:21], v[168:169]
	v_add_f32_dpp v28, v46, v34 row_half_mirror row_mask:0xf bank_mask:0xf
	v_add_f32_dpp v32, v47, v35 row_half_mirror row_mask:0xf bank_mask:0xf
	v_pk_mul_f32 v[22:23], v[22:23], v[170:171]
	v_add_f32_dpp v28, v28, v28 row_ror:8 row_mask:0xf bank_mask:0xf
	v_add_f32_dpp v32, v32, v32 row_ror:8 row_mask:0xf bank_mask:0xf
	v_pk_mul_f32 v[24:25], v[24:25], v[168:169]
	v_add_f32_dpp v28, v28, v28 quad_perm:[1,0,3,2] row_mask:0xf bank_mask:0xf
	v_add_f32_dpp v32, v32, v32 quad_perm:[1,0,3,2] row_mask:0xf bank_mask:0xf
	v_pk_mul_f32 v[26:27], v[26:27], v[170:171]
	v_add_f32_dpp v28, v28, v28 quad_perm:[2,3,0,1] row_mask:0xf bank_mask:0xf
	v_add_f32_dpp v32, v32, v32 quad_perm:[2,3,0,1] row_mask:0xf bank_mask:0xf
	v_pk_fma_f32 v[20:21], v[180:181], v[8:9], v[20:21] op_sel_hi:[1,0,1]
	v_mov_b32_dpp v30, v28 row_half_mirror row_mask:0xf bank_mask:0xf
	v_pk_fma_f32 v[22:23], v[182:183], v[8:9], v[22:23] op_sel_hi:[1,0,1]
	v_pk_fma_f32 v[24:25], v[180:181], v[10:11], v[24:25] op_sel_hi:[1,0,1]
	v_pk_fma_f32 v[26:27], v[182:183], v[10:11], v[26:27] op_sel_hi:[1,0,1]
	v_pk_fma_f32 v[20:21], v[88:89], v[28:29], v[20:21] op_sel_hi:[1,0,1] neg_lo:[0,1,0] neg_hi:[0,1,0]
	v_pk_fma_f32 v[22:23], v[90:91], v[28:29], v[22:23] op_sel_hi:[1,0,1] neg_lo:[0,1,0] neg_hi:[0,1,0]
	v_pk_fma_f32 v[24:25], v[88:89], v[30:31], v[24:25] op_sel_hi:[1,0,1] neg_lo:[0,1,0] neg_hi:[0,1,0]
	v_pk_fma_f32 v[26:27], v[90:91], v[30:31], v[26:27] op_sel_hi:[1,0,1] neg_lo:[0,1,0] neg_hi:[0,1,0]
	v_add_f32_e32 v39, v32, v9
	ds_write_b32 v102, v39 offset:1408
	ds_read_b128 v[144:147], v195 offset:3328
	ds_read_b128 v[156:159], v195 offset:11520
	ds_read_b128 v[180:183], v195 offset:19712
	ds_read_b128 v[88:91], v195 offset:36096
	ds_read_b64 v[8:9], v196 offset:6656
	ds_read_b32 v10, v36 offset:6656
	s_waitcnt lgkmcnt(7)
	v_pk_mul_f32 v[46:47], v[24:25], v[140:141] op_sel_hi:[0,1]
	v_pk_mul_f32 v[34:35], v[20:21], v[140:141] op_sel_hi:[0,1]
	v_pk_fma_f32 v[46:47], v[24:25], v[142:143], v[46:47] op_sel:[1,0,0] op_sel_hi:[1,1,1]
	v_pk_fma_f32 v[34:35], v[20:21], v[142:143], v[34:35] op_sel:[1,0,0] op_sel_hi:[1,1,1]
	v_pk_fma_f32 v[46:47], v[26:27], v[152:153], v[46:47] op_sel_hi:[0,1,1]
	v_pk_fma_f32 v[34:35], v[22:23], v[152:153], v[34:35] op_sel_hi:[0,1,1]
	v_pk_fma_f32 v[46:47], v[26:27], v[154:155], v[46:47] op_sel:[1,0,0] op_sel_hi:[1,1,1]
	v_pk_fma_f32 v[34:35], v[22:23], v[154:155], v[34:35] op_sel:[1,0,0] op_sel_hi:[1,1,1]
	v_pk_fma_f32 v[20:21], v[176:177], v[4:5], v[20:21] op_sel_hi:[1,0,1]
	v_add_f32_dpp v28, v46, v34 row_half_mirror row_mask:0xf bank_mask:0xf
	v_add_f32_dpp v32, v47, v35 row_half_mirror row_mask:0xf bank_mask:0xf
	v_pk_fma_f32 v[22:23], v[178:179], v[4:5], v[22:23] op_sel_hi:[1,0,1]
	v_add_f32_dpp v28, v28, v28 row_ror:8 row_mask:0xf bank_mask:0xf
	v_add_f32_dpp v32, v32, v32 row_ror:8 row_mask:0xf bank_mask:0xf
	v_pk_fma_f32 v[24:25], v[176:177], v[6:7], v[24:25] op_sel_hi:[1,0,1]
	v_add_f32_dpp v28, v28, v28 quad_perm:[1,0,3,2] row_mask:0xf bank_mask:0xf
	v_add_f32_dpp v32, v32, v32 quad_perm:[1,0,3,2] row_mask:0xf bank_mask:0xf
	v_pk_fma_f32 v[26:27], v[178:179], v[6:7], v[26:27] op_sel_hi:[1,0,1]
	v_add_f32_dpp v28, v28, v28 quad_perm:[2,3,0,1] row_mask:0xf bank_mask:0xf
	v_add_f32_dpp v32, v32, v32 quad_perm:[2,3,0,1] row_mask:0xf bank_mask:0xf
	v_add_f32_e32 v39, v32, v5
	v_mov_b32_dpp v30, v28 row_half_mirror row_mask:0xf bank_mask:0xf
	v_pk_fma_f32 v[20:21], v[84:85], v[28:29], v[20:21] op_sel_hi:[1,0,1] neg_lo:[0,1,0] neg_hi:[0,1,0]
	v_pk_fma_f32 v[22:23], v[86:87], v[28:29], v[22:23] op_sel_hi:[1,0,1] neg_lo:[0,1,0] neg_hi:[0,1,0]
	v_pk_fma_f32 v[24:25], v[84:85], v[30:31], v[24:25] op_sel_hi:[1,0,1] neg_lo:[0,1,0] neg_hi:[0,1,0]
	v_pk_fma_f32 v[26:27], v[86:87], v[30:31], v[26:27] op_sel_hi:[1,0,1] neg_lo:[0,1,0] neg_hi:[0,1,0]
	ds_write_b32 v102, v39 offset:1536
	ds_read_b128 v[140:143], v195 offset:3584
	ds_read_b128 v[152:155], v195 offset:11776
	ds_read_b128 v[176:179], v195 offset:19968
	ds_read_b128 v[84:87], v195 offset:36352
	ds_read_b64 v[4:5], v196 offset:7168
	ds_read_b32 v6, v36 offset:7168
	s_waitcnt lgkmcnt(7)
	v_pk_mul_f32 v[46:47], v[24:25], v[144:145] op_sel_hi:[0,1]
	v_pk_mul_f32 v[34:35], v[20:21], v[144:145] op_sel_hi:[0,1]
	v_pk_fma_f32 v[46:47], v[24:25], v[146:147], v[46:47] op_sel:[1,0,0] op_sel_hi:[1,1,1]
	v_pk_fma_f32 v[34:35], v[20:21], v[146:147], v[34:35] op_sel:[1,0,0] op_sel_hi:[1,1,1]
	v_pk_fma_f32 v[46:47], v[26:27], v[156:157], v[46:47] op_sel_hi:[0,1,1]
	v_pk_fma_f32 v[34:35], v[22:23], v[156:157], v[34:35] op_sel_hi:[0,1,1]
	v_pk_fma_f32 v[46:47], v[26:27], v[158:159], v[46:47] op_sel:[1,0,0] op_sel_hi:[1,1,1]
	v_pk_fma_f32 v[34:35], v[22:23], v[158:159], v[34:35] op_sel:[1,0,0] op_sel_hi:[1,1,1]
	v_pk_fma_f32 v[20:21], v[180:181], v[8:9], v[20:21] op_sel_hi:[1,0,1]
	v_add_f32_dpp v28, v46, v34 row_half_mirror row_mask:0xf bank_mask:0xf
	v_add_f32_dpp v32, v47, v35 row_half_mirror row_mask:0xf bank_mask:0xf
	v_pk_fma_f32 v[22:23], v[182:183], v[8:9], v[22:23] op_sel_hi:[1,0,1]
	v_add_f32_dpp v28, v28, v28 row_ror:8 row_mask:0xf bank_mask:0xf
	v_add_f32_dpp v32, v32, v32 row_ror:8 row_mask:0xf bank_mask:0xf
	v_pk_fma_f32 v[24:25], v[180:181], v[10:11], v[24:25] op_sel_hi:[1,0,1]
	v_add_f32_dpp v28, v28, v28 quad_perm:[1,0,3,2] row_mask:0xf bank_mask:0xf
	v_add_f32_dpp v32, v32, v32 quad_perm:[1,0,3,2] row_mask:0xf bank_mask:0xf
	v_pk_fma_f32 v[26:27], v[182:183], v[10:11], v[26:27] op_sel_hi:[1,0,1]
	v_add_f32_dpp v28, v28, v28 quad_perm:[2,3,0,1] row_mask:0xf bank_mask:0xf
	v_add_f32_dpp v32, v32, v32 quad_perm:[2,3,0,1] row_mask:0xf bank_mask:0xf
	v_add_f32_e32 v39, v32, v9
	v_mov_b32_dpp v30, v28 row_half_mirror row_mask:0xf bank_mask:0xf
	v_pk_fma_f32 v[20:21], v[88:89], v[28:29], v[20:21] op_sel_hi:[1,0,1] neg_lo:[0,1,0] neg_hi:[0,1,0]
	v_pk_fma_f32 v[22:23], v[90:91], v[28:29], v[22:23] op_sel_hi:[1,0,1] neg_lo:[0,1,0] neg_hi:[0,1,0]
	v_pk_fma_f32 v[24:25], v[88:89], v[30:31], v[24:25] op_sel_hi:[1,0,1] neg_lo:[0,1,0] neg_hi:[0,1,0]
	v_pk_fma_f32 v[26:27], v[90:91], v[30:31], v[26:27] op_sel_hi:[1,0,1] neg_lo:[0,1,0] neg_hi:[0,1,0]
	ds_write_b32 v102, v39 offset:1664
	ds_read_b128 v[144:147], v195 offset:3840
	ds_read_b128 v[156:159], v195 offset:12032
	ds_read_b128 v[168:171], v195 offset:28416
	ds_read_b128 v[180:183], v195 offset:20224
	ds_read_b128 v[88:91], v195 offset:36608
	ds_read_b64 v[8:9], v196 offset:7680
	ds_read_b32 v10, v36 offset:7680
	s_waitcnt lgkmcnt(8)
	v_pk_mul_f32 v[46:47], v[24:25], v[140:141] op_sel_hi:[0,1]
	v_pk_mul_f32 v[34:35], v[20:21], v[140:141] op_sel_hi:[0,1]
	v_pk_fma_f32 v[46:47], v[24:25], v[142:143], v[46:47] op_sel:[1,0,0] op_sel_hi:[1,1,1]
	v_pk_fma_f32 v[34:35], v[20:21], v[142:143], v[34:35] op_sel:[1,0,0] op_sel_hi:[1,1,1]
	v_pk_fma_f32 v[46:47], v[26:27], v[152:153], v[46:47] op_sel_hi:[0,1,1]
	v_pk_fma_f32 v[34:35], v[22:23], v[152:153], v[34:35] op_sel_hi:[0,1,1]
	v_pk_fma_f32 v[46:47], v[26:27], v[154:155], v[46:47] op_sel:[1,0,0] op_sel_hi:[1,1,1]
	v_pk_fma_f32 v[34:35], v[22:23], v[154:155], v[34:35] op_sel:[1,0,0] op_sel_hi:[1,1,1]
	v_pk_fma_f32 v[20:21], v[176:177], v[4:5], v[20:21] op_sel_hi:[1,0,1]
	v_add_f32_dpp v28, v46, v34 row_half_mirror row_mask:0xf bank_mask:0xf
	v_add_f32_dpp v32, v47, v35 row_half_mirror row_mask:0xf bank_mask:0xf
	v_pk_fma_f32 v[22:23], v[178:179], v[4:5], v[22:23] op_sel_hi:[1,0,1]
	v_add_f32_dpp v28, v28, v28 row_ror:8 row_mask:0xf bank_mask:0xf
	v_add_f32_dpp v32, v32, v32 row_ror:8 row_mask:0xf bank_mask:0xf
	v_pk_fma_f32 v[24:25], v[176:177], v[6:7], v[24:25] op_sel_hi:[1,0,1]
	v_add_f32_dpp v28, v28, v28 quad_perm:[1,0,3,2] row_mask:0xf bank_mask:0xf
	v_add_f32_dpp v32, v32, v32 quad_perm:[1,0,3,2] row_mask:0xf bank_mask:0xf
	v_pk_fma_f32 v[26:27], v[178:179], v[6:7], v[26:27] op_sel_hi:[1,0,1]
	v_add_f32_dpp v28, v28, v28 quad_perm:[2,3,0,1] row_mask:0xf bank_mask:0xf
	v_add_f32_dpp v32, v32, v32 quad_perm:[2,3,0,1] row_mask:0xf bank_mask:0xf
	v_add_f32_e32 v39, v32, v5
	v_mov_b32_dpp v30, v28 row_half_mirror row_mask:0xf bank_mask:0xf
	v_pk_fma_f32 v[20:21], v[84:85], v[28:29], v[20:21] op_sel_hi:[1,0,1] neg_lo:[0,1,0] neg_hi:[0,1,0]
	v_pk_fma_f32 v[22:23], v[86:87], v[28:29], v[22:23] op_sel_hi:[1,0,1] neg_lo:[0,1,0] neg_hi:[0,1,0]
	v_pk_fma_f32 v[24:25], v[84:85], v[30:31], v[24:25] op_sel_hi:[1,0,1] neg_lo:[0,1,0] neg_hi:[0,1,0]
	v_pk_fma_f32 v[26:27], v[86:87], v[30:31], v[26:27] op_sel_hi:[1,0,1] neg_lo:[0,1,0] neg_hi:[0,1,0]
	ds_write_b32 v102, v39 offset:1792
	ds_read_b128 v[140:143], v195 offset:4096
	ds_read_b128 v[152:155], v195 offset:12288
	ds_read_b128 v[176:179], v195 offset:20480
	ds_read_b128 v[84:87], v195 offset:36864
	ds_read_b64 v[4:5], v196 offset:8192
	ds_read_b32 v6, v36 offset:8192
	s_waitcnt lgkmcnt(7)
	v_pk_mul_f32 v[46:47], v[24:25], v[144:145] op_sel_hi:[0,1]
	v_pk_mul_f32 v[34:35], v[20:21], v[144:145] op_sel_hi:[0,1]
	v_pk_fma_f32 v[46:47], v[24:25], v[146:147], v[46:47] op_sel:[1,0,0] op_sel_hi:[1,1,1]
	v_pk_fma_f32 v[34:35], v[20:21], v[146:147], v[34:35] op_sel:[1,0,0] op_sel_hi:[1,1,1]
	v_pk_fma_f32 v[46:47], v[26:27], v[156:157], v[46:47] op_sel_hi:[0,1,1]
	v_pk_fma_f32 v[34:35], v[22:23], v[156:157], v[34:35] op_sel_hi:[0,1,1]
	v_pk_fma_f32 v[46:47], v[26:27], v[158:159], v[46:47] op_sel:[1,0,0] op_sel_hi:[1,1,1]
	v_pk_fma_f32 v[34:35], v[22:23], v[158:159], v[34:35] op_sel:[1,0,0] op_sel_hi:[1,1,1]
	v_pk_mul_f32 v[20:21], v[20:21], v[168:169]
	v_add_f32_dpp v28, v46, v34 row_half_mirror row_mask:0xf bank_mask:0xf
	v_add_f32_dpp v32, v47, v35 row_half_mirror row_mask:0xf bank_mask:0xf
	v_pk_mul_f32 v[22:23], v[22:23], v[170:171]
	v_add_f32_dpp v28, v28, v28 row_ror:8 row_mask:0xf bank_mask:0xf
	v_add_f32_dpp v32, v32, v32 row_ror:8 row_mask:0xf bank_mask:0xf
	v_pk_mul_f32 v[24:25], v[24:25], v[168:169]
	v_add_f32_dpp v28, v28, v28 quad_perm:[1,0,3,2] row_mask:0xf bank_mask:0xf
	v_add_f32_dpp v32, v32, v32 quad_perm:[1,0,3,2] row_mask:0xf bank_mask:0xf
	v_pk_mul_f32 v[26:27], v[26:27], v[170:171]
	v_add_f32_dpp v28, v28, v28 quad_perm:[2,3,0,1] row_mask:0xf bank_mask:0xf
	v_add_f32_dpp v32, v32, v32 quad_perm:[2,3,0,1] row_mask:0xf bank_mask:0xf
	v_pk_fma_f32 v[20:21], v[180:181], v[8:9], v[20:21] op_sel_hi:[1,0,1]
	v_mov_b32_dpp v30, v28 row_half_mirror row_mask:0xf bank_mask:0xf
	v_pk_fma_f32 v[22:23], v[182:183], v[8:9], v[22:23] op_sel_hi:[1,0,1]
	v_pk_fma_f32 v[24:25], v[180:181], v[10:11], v[24:25] op_sel_hi:[1,0,1]
	v_pk_fma_f32 v[26:27], v[182:183], v[10:11], v[26:27] op_sel_hi:[1,0,1]
	v_pk_fma_f32 v[20:21], v[88:89], v[28:29], v[20:21] op_sel_hi:[1,0,1] neg_lo:[0,1,0] neg_hi:[0,1,0]
	v_pk_fma_f32 v[22:23], v[90:91], v[28:29], v[22:23] op_sel_hi:[1,0,1] neg_lo:[0,1,0] neg_hi:[0,1,0]
	v_pk_fma_f32 v[24:25], v[88:89], v[30:31], v[24:25] op_sel_hi:[1,0,1] neg_lo:[0,1,0] neg_hi:[0,1,0]
	v_pk_fma_f32 v[26:27], v[90:91], v[30:31], v[26:27] op_sel_hi:[1,0,1] neg_lo:[0,1,0] neg_hi:[0,1,0]
	v_add_f32_e32 v39, v32, v9
	ds_write_b32 v102, v39 offset:1920
	ds_read_b128 v[144:147], v195 offset:4352
	ds_read_b128 v[156:159], v195 offset:12544
	ds_read_b128 v[180:183], v195 offset:20736
	ds_read_b128 v[88:91], v195 offset:37120
	ds_read_b64 v[8:9], v196 offset:8704
	ds_read_b32 v10, v36 offset:8704
	s_waitcnt lgkmcnt(7)
	v_pk_mul_f32 v[46:47], v[24:25], v[140:141] op_sel_hi:[0,1]
	v_pk_mul_f32 v[34:35], v[20:21], v[140:141] op_sel_hi:[0,1]
	v_pk_fma_f32 v[46:47], v[24:25], v[142:143], v[46:47] op_sel:[1,0,0] op_sel_hi:[1,1,1]
	v_pk_fma_f32 v[34:35], v[20:21], v[142:143], v[34:35] op_sel:[1,0,0] op_sel_hi:[1,1,1]
	v_pk_fma_f32 v[46:47], v[26:27], v[152:153], v[46:47] op_sel_hi:[0,1,1]
	v_pk_fma_f32 v[34:35], v[22:23], v[152:153], v[34:35] op_sel_hi:[0,1,1]
	v_pk_fma_f32 v[46:47], v[26:27], v[154:155], v[46:47] op_sel:[1,0,0] op_sel_hi:[1,1,1]
	v_pk_fma_f32 v[34:35], v[22:23], v[154:155], v[34:35] op_sel:[1,0,0] op_sel_hi:[1,1,1]
	v_pk_fma_f32 v[20:21], v[176:177], v[4:5], v[20:21] op_sel_hi:[1,0,1]
	v_add_f32_dpp v28, v46, v34 row_half_mirror row_mask:0xf bank_mask:0xf
	v_add_f32_dpp v32, v47, v35 row_half_mirror row_mask:0xf bank_mask:0xf
	v_pk_fma_f32 v[22:23], v[178:179], v[4:5], v[22:23] op_sel_hi:[1,0,1]
	v_add_f32_dpp v28, v28, v28 row_ror:8 row_mask:0xf bank_mask:0xf
	v_add_f32_dpp v32, v32, v32 row_ror:8 row_mask:0xf bank_mask:0xf
	v_pk_fma_f32 v[24:25], v[176:177], v[6:7], v[24:25] op_sel_hi:[1,0,1]
	v_add_f32_dpp v28, v28, v28 quad_perm:[1,0,3,2] row_mask:0xf bank_mask:0xf
	v_add_f32_dpp v32, v32, v32 quad_perm:[1,0,3,2] row_mask:0xf bank_mask:0xf
	v_pk_fma_f32 v[26:27], v[178:179], v[6:7], v[26:27] op_sel_hi:[1,0,1]
	v_add_f32_dpp v28, v28, v28 quad_perm:[2,3,0,1] row_mask:0xf bank_mask:0xf
	v_add_f32_dpp v32, v32, v32 quad_perm:[2,3,0,1] row_mask:0xf bank_mask:0xf
	v_add_f32_e32 v39, v32, v5
	v_mov_b32_dpp v30, v28 row_half_mirror row_mask:0xf bank_mask:0xf
	v_pk_fma_f32 v[20:21], v[84:85], v[28:29], v[20:21] op_sel_hi:[1,0,1] neg_lo:[0,1,0] neg_hi:[0,1,0]
	v_pk_fma_f32 v[22:23], v[86:87], v[28:29], v[22:23] op_sel_hi:[1,0,1] neg_lo:[0,1,0] neg_hi:[0,1,0]
	v_pk_fma_f32 v[24:25], v[84:85], v[30:31], v[24:25] op_sel_hi:[1,0,1] neg_lo:[0,1,0] neg_hi:[0,1,0]
	v_pk_fma_f32 v[26:27], v[86:87], v[30:31], v[26:27] op_sel_hi:[1,0,1] neg_lo:[0,1,0] neg_hi:[0,1,0]
	ds_write_b32 v102, v39 offset:2048
	ds_read_b128 v[140:143], v195 offset:4608
	ds_read_b128 v[152:155], v195 offset:12800
	ds_read_b128 v[176:179], v195 offset:20992
	ds_read_b128 v[84:87], v195 offset:37376
	ds_read_b64 v[4:5], v196 offset:9216
	ds_read_b32 v6, v36 offset:9216
	s_waitcnt lgkmcnt(7)
	v_pk_mul_f32 v[46:47], v[24:25], v[144:145] op_sel_hi:[0,1]
	v_pk_mul_f32 v[34:35], v[20:21], v[144:145] op_sel_hi:[0,1]
	v_pk_fma_f32 v[46:47], v[24:25], v[146:147], v[46:47] op_sel:[1,0,0] op_sel_hi:[1,1,1]
	v_pk_fma_f32 v[34:35], v[20:21], v[146:147], v[34:35] op_sel:[1,0,0] op_sel_hi:[1,1,1]
	v_pk_fma_f32 v[46:47], v[26:27], v[156:157], v[46:47] op_sel_hi:[0,1,1]
	v_pk_fma_f32 v[34:35], v[22:23], v[156:157], v[34:35] op_sel_hi:[0,1,1]
	v_pk_fma_f32 v[46:47], v[26:27], v[158:159], v[46:47] op_sel:[1,0,0] op_sel_hi:[1,1,1]
	v_pk_fma_f32 v[34:35], v[22:23], v[158:159], v[34:35] op_sel:[1,0,0] op_sel_hi:[1,1,1]
	v_pk_fma_f32 v[20:21], v[180:181], v[8:9], v[20:21] op_sel_hi:[1,0,1]
	v_add_f32_dpp v28, v46, v34 row_half_mirror row_mask:0xf bank_mask:0xf
	v_add_f32_dpp v32, v47, v35 row_half_mirror row_mask:0xf bank_mask:0xf
	v_pk_fma_f32 v[22:23], v[182:183], v[8:9], v[22:23] op_sel_hi:[1,0,1]
	v_add_f32_dpp v28, v28, v28 row_ror:8 row_mask:0xf bank_mask:0xf
	v_add_f32_dpp v32, v32, v32 row_ror:8 row_mask:0xf bank_mask:0xf
	v_pk_fma_f32 v[24:25], v[180:181], v[10:11], v[24:25] op_sel_hi:[1,0,1]
	v_add_f32_dpp v28, v28, v28 quad_perm:[1,0,3,2] row_mask:0xf bank_mask:0xf
	v_add_f32_dpp v32, v32, v32 quad_perm:[1,0,3,2] row_mask:0xf bank_mask:0xf
	v_pk_fma_f32 v[26:27], v[182:183], v[10:11], v[26:27] op_sel_hi:[1,0,1]
	v_add_f32_dpp v28, v28, v28 quad_perm:[2,3,0,1] row_mask:0xf bank_mask:0xf
	v_add_f32_dpp v32, v32, v32 quad_perm:[2,3,0,1] row_mask:0xf bank_mask:0xf
	v_add_f32_e32 v39, v32, v9
	v_mov_b32_dpp v30, v28 row_half_mirror row_mask:0xf bank_mask:0xf
	v_pk_fma_f32 v[20:21], v[88:89], v[28:29], v[20:21] op_sel_hi:[1,0,1] neg_lo:[0,1,0] neg_hi:[0,1,0]
	v_pk_fma_f32 v[22:23], v[90:91], v[28:29], v[22:23] op_sel_hi:[1,0,1] neg_lo:[0,1,0] neg_hi:[0,1,0]
	v_pk_fma_f32 v[24:25], v[88:89], v[30:31], v[24:25] op_sel_hi:[1,0,1] neg_lo:[0,1,0] neg_hi:[0,1,0]
	v_pk_fma_f32 v[26:27], v[90:91], v[30:31], v[26:27] op_sel_hi:[1,0,1] neg_lo:[0,1,0] neg_hi:[0,1,0]
	ds_write_b32 v102, v39 offset:2176
	ds_read_b128 v[144:147], v195 offset:4864
	ds_read_b128 v[156:159], v195 offset:13056
	ds_read_b128 v[168:171], v195 offset:29440
	ds_read_b128 v[180:183], v195 offset:21248
	ds_read_b128 v[88:91], v195 offset:37632
	ds_read_b64 v[8:9], v196 offset:9728
	ds_read_b32 v10, v36 offset:9728
	s_waitcnt lgkmcnt(8)
	v_pk_mul_f32 v[46:47], v[24:25], v[140:141] op_sel_hi:[0,1]
	v_pk_mul_f32 v[34:35], v[20:21], v[140:141] op_sel_hi:[0,1]
	v_pk_fma_f32 v[46:47], v[24:25], v[142:143], v[46:47] op_sel:[1,0,0] op_sel_hi:[1,1,1]
	v_pk_fma_f32 v[34:35], v[20:21], v[142:143], v[34:35] op_sel:[1,0,0] op_sel_hi:[1,1,1]
	v_pk_fma_f32 v[46:47], v[26:27], v[152:153], v[46:47] op_sel_hi:[0,1,1]
	v_pk_fma_f32 v[34:35], v[22:23], v[152:153], v[34:35] op_sel_hi:[0,1,1]
	v_pk_fma_f32 v[46:47], v[26:27], v[154:155], v[46:47] op_sel:[1,0,0] op_sel_hi:[1,1,1]
	v_pk_fma_f32 v[34:35], v[22:23], v[154:155], v[34:35] op_sel:[1,0,0] op_sel_hi:[1,1,1]
	v_pk_fma_f32 v[20:21], v[176:177], v[4:5], v[20:21] op_sel_hi:[1,0,1]
	v_add_f32_dpp v28, v46, v34 row_half_mirror row_mask:0xf bank_mask:0xf
	v_add_f32_dpp v32, v47, v35 row_half_mirror row_mask:0xf bank_mask:0xf
	v_pk_fma_f32 v[22:23], v[178:179], v[4:5], v[22:23] op_sel_hi:[1,0,1]
	v_add_f32_dpp v28, v28, v28 row_ror:8 row_mask:0xf bank_mask:0xf
	v_add_f32_dpp v32, v32, v32 row_ror:8 row_mask:0xf bank_mask:0xf
	v_pk_fma_f32 v[24:25], v[176:177], v[6:7], v[24:25] op_sel_hi:[1,0,1]
	v_add_f32_dpp v28, v28, v28 quad_perm:[1,0,3,2] row_mask:0xf bank_mask:0xf
	v_add_f32_dpp v32, v32, v32 quad_perm:[1,0,3,2] row_mask:0xf bank_mask:0xf
	v_pk_fma_f32 v[26:27], v[178:179], v[6:7], v[26:27] op_sel_hi:[1,0,1]
	v_add_f32_dpp v28, v28, v28 quad_perm:[2,3,0,1] row_mask:0xf bank_mask:0xf
	v_add_f32_dpp v32, v32, v32 quad_perm:[2,3,0,1] row_mask:0xf bank_mask:0xf
	v_add_f32_e32 v39, v32, v5
	v_mov_b32_dpp v30, v28 row_half_mirror row_mask:0xf bank_mask:0xf
	v_pk_fma_f32 v[20:21], v[84:85], v[28:29], v[20:21] op_sel_hi:[1,0,1] neg_lo:[0,1,0] neg_hi:[0,1,0]
	v_pk_fma_f32 v[22:23], v[86:87], v[28:29], v[22:23] op_sel_hi:[1,0,1] neg_lo:[0,1,0] neg_hi:[0,1,0]
	v_pk_fma_f32 v[24:25], v[84:85], v[30:31], v[24:25] op_sel_hi:[1,0,1] neg_lo:[0,1,0] neg_hi:[0,1,0]
	v_pk_fma_f32 v[26:27], v[86:87], v[30:31], v[26:27] op_sel_hi:[1,0,1] neg_lo:[0,1,0] neg_hi:[0,1,0]
	ds_write_b32 v102, v39 offset:2304
	ds_read_b128 v[140:143], v195 offset:5120
	ds_read_b128 v[152:155], v195 offset:13312
	ds_read_b128 v[176:179], v195 offset:21504
	ds_read_b128 v[84:87], v195 offset:37888
	ds_read_b64 v[4:5], v196 offset:10240
	ds_read_b32 v6, v36 offset:10240
	s_waitcnt lgkmcnt(7)
	v_pk_mul_f32 v[46:47], v[24:25], v[144:145] op_sel_hi:[0,1]
	v_pk_mul_f32 v[34:35], v[20:21], v[144:145] op_sel_hi:[0,1]
	v_pk_fma_f32 v[46:47], v[24:25], v[146:147], v[46:47] op_sel:[1,0,0] op_sel_hi:[1,1,1]
	v_pk_fma_f32 v[34:35], v[20:21], v[146:147], v[34:35] op_sel:[1,0,0] op_sel_hi:[1,1,1]
	v_pk_fma_f32 v[46:47], v[26:27], v[156:157], v[46:47] op_sel_hi:[0,1,1]
	v_pk_fma_f32 v[34:35], v[22:23], v[156:157], v[34:35] op_sel_hi:[0,1,1]
	v_pk_fma_f32 v[46:47], v[26:27], v[158:159], v[46:47] op_sel:[1,0,0] op_sel_hi:[1,1,1]
	v_pk_fma_f32 v[34:35], v[22:23], v[158:159], v[34:35] op_sel:[1,0,0] op_sel_hi:[1,1,1]
	v_pk_mul_f32 v[20:21], v[20:21], v[168:169]
	v_add_f32_dpp v28, v46, v34 row_half_mirror row_mask:0xf bank_mask:0xf
	v_add_f32_dpp v32, v47, v35 row_half_mirror row_mask:0xf bank_mask:0xf
	v_pk_mul_f32 v[22:23], v[22:23], v[170:171]
	v_add_f32_dpp v28, v28, v28 row_ror:8 row_mask:0xf bank_mask:0xf
	v_add_f32_dpp v32, v32, v32 row_ror:8 row_mask:0xf bank_mask:0xf
	v_pk_mul_f32 v[24:25], v[24:25], v[168:169]
	v_add_f32_dpp v28, v28, v28 quad_perm:[1,0,3,2] row_mask:0xf bank_mask:0xf
	v_add_f32_dpp v32, v32, v32 quad_perm:[1,0,3,2] row_mask:0xf bank_mask:0xf
	v_pk_mul_f32 v[26:27], v[26:27], v[170:171]
	v_add_f32_dpp v28, v28, v28 quad_perm:[2,3,0,1] row_mask:0xf bank_mask:0xf
	v_add_f32_dpp v32, v32, v32 quad_perm:[2,3,0,1] row_mask:0xf bank_mask:0xf
	v_pk_fma_f32 v[20:21], v[180:181], v[8:9], v[20:21] op_sel_hi:[1,0,1]
	v_mov_b32_dpp v30, v28 row_half_mirror row_mask:0xf bank_mask:0xf
	v_pk_fma_f32 v[22:23], v[182:183], v[8:9], v[22:23] op_sel_hi:[1,0,1]
	v_pk_fma_f32 v[24:25], v[180:181], v[10:11], v[24:25] op_sel_hi:[1,0,1]
	v_pk_fma_f32 v[26:27], v[182:183], v[10:11], v[26:27] op_sel_hi:[1,0,1]
	v_pk_fma_f32 v[20:21], v[88:89], v[28:29], v[20:21] op_sel_hi:[1,0,1] neg_lo:[0,1,0] neg_hi:[0,1,0]
	v_pk_fma_f32 v[22:23], v[90:91], v[28:29], v[22:23] op_sel_hi:[1,0,1] neg_lo:[0,1,0] neg_hi:[0,1,0]
	v_pk_fma_f32 v[24:25], v[88:89], v[30:31], v[24:25] op_sel_hi:[1,0,1] neg_lo:[0,1,0] neg_hi:[0,1,0]
	v_pk_fma_f32 v[26:27], v[90:91], v[30:31], v[26:27] op_sel_hi:[1,0,1] neg_lo:[0,1,0] neg_hi:[0,1,0]
	v_add_f32_e32 v39, v32, v9
	ds_write_b32 v102, v39 offset:2432
	ds_read_b128 v[144:147], v195 offset:5376
	ds_read_b128 v[156:159], v195 offset:13568
	ds_read_b128 v[180:183], v195 offset:21760
	ds_read_b128 v[88:91], v195 offset:38144
	ds_read_b64 v[8:9], v196 offset:10752
	ds_read_b32 v10, v36 offset:10752
	s_waitcnt lgkmcnt(7)
	v_pk_mul_f32 v[46:47], v[24:25], v[140:141] op_sel_hi:[0,1]
	v_pk_mul_f32 v[34:35], v[20:21], v[140:141] op_sel_hi:[0,1]
	v_pk_fma_f32 v[46:47], v[24:25], v[142:143], v[46:47] op_sel:[1,0,0] op_sel_hi:[1,1,1]
	v_pk_fma_f32 v[34:35], v[20:21], v[142:143], v[34:35] op_sel:[1,0,0] op_sel_hi:[1,1,1]
	v_pk_fma_f32 v[46:47], v[26:27], v[152:153], v[46:47] op_sel_hi:[0,1,1]
	v_pk_fma_f32 v[34:35], v[22:23], v[152:153], v[34:35] op_sel_hi:[0,1,1]
	v_pk_fma_f32 v[46:47], v[26:27], v[154:155], v[46:47] op_sel:[1,0,0] op_sel_hi:[1,1,1]
	v_pk_fma_f32 v[34:35], v[22:23], v[154:155], v[34:35] op_sel:[1,0,0] op_sel_hi:[1,1,1]
	v_pk_fma_f32 v[20:21], v[176:177], v[4:5], v[20:21] op_sel_hi:[1,0,1]
	v_add_f32_dpp v28, v46, v34 row_half_mirror row_mask:0xf bank_mask:0xf
	v_add_f32_dpp v32, v47, v35 row_half_mirror row_mask:0xf bank_mask:0xf
	v_pk_fma_f32 v[22:23], v[178:179], v[4:5], v[22:23] op_sel_hi:[1,0,1]
	v_add_f32_dpp v28, v28, v28 row_ror:8 row_mask:0xf bank_mask:0xf
	v_add_f32_dpp v32, v32, v32 row_ror:8 row_mask:0xf bank_mask:0xf
	v_pk_fma_f32 v[24:25], v[176:177], v[6:7], v[24:25] op_sel_hi:[1,0,1]
	v_add_f32_dpp v28, v28, v28 quad_perm:[1,0,3,2] row_mask:0xf bank_mask:0xf
	v_add_f32_dpp v32, v32, v32 quad_perm:[1,0,3,2] row_mask:0xf bank_mask:0xf
	v_pk_fma_f32 v[26:27], v[178:179], v[6:7], v[26:27] op_sel_hi:[1,0,1]
	v_add_f32_dpp v28, v28, v28 quad_perm:[2,3,0,1] row_mask:0xf bank_mask:0xf
	v_add_f32_dpp v32, v32, v32 quad_perm:[2,3,0,1] row_mask:0xf bank_mask:0xf
	v_add_f32_e32 v39, v32, v5
	v_mov_b32_dpp v30, v28 row_half_mirror row_mask:0xf bank_mask:0xf
	v_pk_fma_f32 v[20:21], v[84:85], v[28:29], v[20:21] op_sel_hi:[1,0,1] neg_lo:[0,1,0] neg_hi:[0,1,0]
	v_pk_fma_f32 v[22:23], v[86:87], v[28:29], v[22:23] op_sel_hi:[1,0,1] neg_lo:[0,1,0] neg_hi:[0,1,0]
	v_pk_fma_f32 v[24:25], v[84:85], v[30:31], v[24:25] op_sel_hi:[1,0,1] neg_lo:[0,1,0] neg_hi:[0,1,0]
	v_pk_fma_f32 v[26:27], v[86:87], v[30:31], v[26:27] op_sel_hi:[1,0,1] neg_lo:[0,1,0] neg_hi:[0,1,0]
	ds_write_b32 v102, v39 offset:2560
	ds_read_b128 v[140:143], v195 offset:5632
	ds_read_b128 v[152:155], v195 offset:13824
	ds_read_b128 v[176:179], v195 offset:22016
	ds_read_b128 v[84:87], v195 offset:38400
	ds_read_b64 v[4:5], v196 offset:11264
	ds_read_b32 v6, v36 offset:11264
	s_waitcnt lgkmcnt(7)
	v_pk_mul_f32 v[46:47], v[24:25], v[144:145] op_sel_hi:[0,1]
	v_pk_mul_f32 v[34:35], v[20:21], v[144:145] op_sel_hi:[0,1]
	v_pk_fma_f32 v[46:47], v[24:25], v[146:147], v[46:47] op_sel:[1,0,0] op_sel_hi:[1,1,1]
	v_pk_fma_f32 v[34:35], v[20:21], v[146:147], v[34:35] op_sel:[1,0,0] op_sel_hi:[1,1,1]
	v_pk_fma_f32 v[46:47], v[26:27], v[156:157], v[46:47] op_sel_hi:[0,1,1]
	v_pk_fma_f32 v[34:35], v[22:23], v[156:157], v[34:35] op_sel_hi:[0,1,1]
	v_pk_fma_f32 v[46:47], v[26:27], v[158:159], v[46:47] op_sel:[1,0,0] op_sel_hi:[1,1,1]
	v_pk_fma_f32 v[34:35], v[22:23], v[158:159], v[34:35] op_sel:[1,0,0] op_sel_hi:[1,1,1]
	v_pk_fma_f32 v[20:21], v[180:181], v[8:9], v[20:21] op_sel_hi:[1,0,1]
	v_add_f32_dpp v28, v46, v34 row_half_mirror row_mask:0xf bank_mask:0xf
	v_add_f32_dpp v32, v47, v35 row_half_mirror row_mask:0xf bank_mask:0xf
	v_pk_fma_f32 v[22:23], v[182:183], v[8:9], v[22:23] op_sel_hi:[1,0,1]
	v_add_f32_dpp v28, v28, v28 row_ror:8 row_mask:0xf bank_mask:0xf
	v_add_f32_dpp v32, v32, v32 row_ror:8 row_mask:0xf bank_mask:0xf
	v_pk_fma_f32 v[24:25], v[180:181], v[10:11], v[24:25] op_sel_hi:[1,0,1]
	v_add_f32_dpp v28, v28, v28 quad_perm:[1,0,3,2] row_mask:0xf bank_mask:0xf
	v_add_f32_dpp v32, v32, v32 quad_perm:[1,0,3,2] row_mask:0xf bank_mask:0xf
	v_pk_fma_f32 v[26:27], v[182:183], v[10:11], v[26:27] op_sel_hi:[1,0,1]
	v_add_f32_dpp v28, v28, v28 quad_perm:[2,3,0,1] row_mask:0xf bank_mask:0xf
	v_add_f32_dpp v32, v32, v32 quad_perm:[2,3,0,1] row_mask:0xf bank_mask:0xf
	v_add_f32_e32 v39, v32, v9
	v_mov_b32_dpp v30, v28 row_half_mirror row_mask:0xf bank_mask:0xf
	v_pk_fma_f32 v[20:21], v[88:89], v[28:29], v[20:21] op_sel_hi:[1,0,1] neg_lo:[0,1,0] neg_hi:[0,1,0]
	v_pk_fma_f32 v[22:23], v[90:91], v[28:29], v[22:23] op_sel_hi:[1,0,1] neg_lo:[0,1,0] neg_hi:[0,1,0]
	v_pk_fma_f32 v[24:25], v[88:89], v[30:31], v[24:25] op_sel_hi:[1,0,1] neg_lo:[0,1,0] neg_hi:[0,1,0]
	v_pk_fma_f32 v[26:27], v[90:91], v[30:31], v[26:27] op_sel_hi:[1,0,1] neg_lo:[0,1,0] neg_hi:[0,1,0]
	ds_write_b32 v102, v39 offset:2688
	ds_read_b128 v[144:147], v195 offset:5888
	ds_read_b128 v[156:159], v195 offset:14080
	ds_read_b128 v[168:171], v195 offset:30464
	ds_read_b128 v[180:183], v195 offset:22272
	ds_read_b128 v[88:91], v195 offset:38656
	ds_read_b64 v[8:9], v196 offset:11776
	ds_read_b32 v10, v36 offset:11776
	s_waitcnt lgkmcnt(8)
	v_pk_mul_f32 v[46:47], v[24:25], v[140:141] op_sel_hi:[0,1]
	v_pk_mul_f32 v[34:35], v[20:21], v[140:141] op_sel_hi:[0,1]
	v_pk_fma_f32 v[46:47], v[24:25], v[142:143], v[46:47] op_sel:[1,0,0] op_sel_hi:[1,1,1]
	v_pk_fma_f32 v[34:35], v[20:21], v[142:143], v[34:35] op_sel:[1,0,0] op_sel_hi:[1,1,1]
	v_pk_fma_f32 v[46:47], v[26:27], v[152:153], v[46:47] op_sel_hi:[0,1,1]
	v_pk_fma_f32 v[34:35], v[22:23], v[152:153], v[34:35] op_sel_hi:[0,1,1]
	v_pk_fma_f32 v[46:47], v[26:27], v[154:155], v[46:47] op_sel:[1,0,0] op_sel_hi:[1,1,1]
	v_pk_fma_f32 v[34:35], v[22:23], v[154:155], v[34:35] op_sel:[1,0,0] op_sel_hi:[1,1,1]
	v_pk_fma_f32 v[20:21], v[176:177], v[4:5], v[20:21] op_sel_hi:[1,0,1]
	v_add_f32_dpp v28, v46, v34 row_half_mirror row_mask:0xf bank_mask:0xf
	v_add_f32_dpp v32, v47, v35 row_half_mirror row_mask:0xf bank_mask:0xf
	v_pk_fma_f32 v[22:23], v[178:179], v[4:5], v[22:23] op_sel_hi:[1,0,1]
	v_add_f32_dpp v28, v28, v28 row_ror:8 row_mask:0xf bank_mask:0xf
	v_add_f32_dpp v32, v32, v32 row_ror:8 row_mask:0xf bank_mask:0xf
	v_pk_fma_f32 v[24:25], v[176:177], v[6:7], v[24:25] op_sel_hi:[1,0,1]
	v_add_f32_dpp v28, v28, v28 quad_perm:[1,0,3,2] row_mask:0xf bank_mask:0xf
	v_add_f32_dpp v32, v32, v32 quad_perm:[1,0,3,2] row_mask:0xf bank_mask:0xf
	v_pk_fma_f32 v[26:27], v[178:179], v[6:7], v[26:27] op_sel_hi:[1,0,1]
	v_add_f32_dpp v28, v28, v28 quad_perm:[2,3,0,1] row_mask:0xf bank_mask:0xf
	v_add_f32_dpp v32, v32, v32 quad_perm:[2,3,0,1] row_mask:0xf bank_mask:0xf
	v_add_f32_e32 v39, v32, v5
	v_mov_b32_dpp v30, v28 row_half_mirror row_mask:0xf bank_mask:0xf
	v_pk_fma_f32 v[20:21], v[84:85], v[28:29], v[20:21] op_sel_hi:[1,0,1] neg_lo:[0,1,0] neg_hi:[0,1,0]
	v_pk_fma_f32 v[22:23], v[86:87], v[28:29], v[22:23] op_sel_hi:[1,0,1] neg_lo:[0,1,0] neg_hi:[0,1,0]
	v_pk_fma_f32 v[24:25], v[84:85], v[30:31], v[24:25] op_sel_hi:[1,0,1] neg_lo:[0,1,0] neg_hi:[0,1,0]
	v_pk_fma_f32 v[26:27], v[86:87], v[30:31], v[26:27] op_sel_hi:[1,0,1] neg_lo:[0,1,0] neg_hi:[0,1,0]
	ds_write_b32 v102, v39 offset:2816
	ds_read_b128 v[140:143], v195 offset:6144
	ds_read_b128 v[152:155], v195 offset:14336
	ds_read_b128 v[176:179], v195 offset:22528
	ds_read_b128 v[84:87], v195 offset:38912
	ds_read_b64 v[4:5], v196 offset:12288
	ds_read_b32 v6, v36 offset:12288
	s_waitcnt lgkmcnt(7)
	v_pk_mul_f32 v[46:47], v[24:25], v[144:145] op_sel_hi:[0,1]
	v_pk_mul_f32 v[34:35], v[20:21], v[144:145] op_sel_hi:[0,1]
	v_pk_fma_f32 v[46:47], v[24:25], v[146:147], v[46:47] op_sel:[1,0,0] op_sel_hi:[1,1,1]
	v_pk_fma_f32 v[34:35], v[20:21], v[146:147], v[34:35] op_sel:[1,0,0] op_sel_hi:[1,1,1]
	v_pk_fma_f32 v[46:47], v[26:27], v[156:157], v[46:47] op_sel_hi:[0,1,1]
	v_pk_fma_f32 v[34:35], v[22:23], v[156:157], v[34:35] op_sel_hi:[0,1,1]
	v_pk_fma_f32 v[46:47], v[26:27], v[158:159], v[46:47] op_sel:[1,0,0] op_sel_hi:[1,1,1]
	v_pk_fma_f32 v[34:35], v[22:23], v[158:159], v[34:35] op_sel:[1,0,0] op_sel_hi:[1,1,1]
	v_pk_mul_f32 v[20:21], v[20:21], v[168:169]
	v_add_f32_dpp v28, v46, v34 row_half_mirror row_mask:0xf bank_mask:0xf
	v_add_f32_dpp v32, v47, v35 row_half_mirror row_mask:0xf bank_mask:0xf
	v_pk_mul_f32 v[22:23], v[22:23], v[170:171]
	v_add_f32_dpp v28, v28, v28 row_ror:8 row_mask:0xf bank_mask:0xf
	v_add_f32_dpp v32, v32, v32 row_ror:8 row_mask:0xf bank_mask:0xf
	v_pk_mul_f32 v[24:25], v[24:25], v[168:169]
	v_add_f32_dpp v28, v28, v28 quad_perm:[1,0,3,2] row_mask:0xf bank_mask:0xf
	v_add_f32_dpp v32, v32, v32 quad_perm:[1,0,3,2] row_mask:0xf bank_mask:0xf
	v_pk_mul_f32 v[26:27], v[26:27], v[170:171]
	v_add_f32_dpp v28, v28, v28 quad_perm:[2,3,0,1] row_mask:0xf bank_mask:0xf
	v_add_f32_dpp v32, v32, v32 quad_perm:[2,3,0,1] row_mask:0xf bank_mask:0xf
	v_pk_fma_f32 v[20:21], v[180:181], v[8:9], v[20:21] op_sel_hi:[1,0,1]
	v_mov_b32_dpp v30, v28 row_half_mirror row_mask:0xf bank_mask:0xf
	v_pk_fma_f32 v[22:23], v[182:183], v[8:9], v[22:23] op_sel_hi:[1,0,1]
	v_pk_fma_f32 v[24:25], v[180:181], v[10:11], v[24:25] op_sel_hi:[1,0,1]
	v_pk_fma_f32 v[26:27], v[182:183], v[10:11], v[26:27] op_sel_hi:[1,0,1]
	v_pk_fma_f32 v[20:21], v[88:89], v[28:29], v[20:21] op_sel_hi:[1,0,1] neg_lo:[0,1,0] neg_hi:[0,1,0]
	v_pk_fma_f32 v[22:23], v[90:91], v[28:29], v[22:23] op_sel_hi:[1,0,1] neg_lo:[0,1,0] neg_hi:[0,1,0]
	v_pk_fma_f32 v[24:25], v[88:89], v[30:31], v[24:25] op_sel_hi:[1,0,1] neg_lo:[0,1,0] neg_hi:[0,1,0]
	v_pk_fma_f32 v[26:27], v[90:91], v[30:31], v[26:27] op_sel_hi:[1,0,1] neg_lo:[0,1,0] neg_hi:[0,1,0]
	v_add_f32_e32 v39, v32, v9
	ds_write_b32 v102, v39 offset:2944
	ds_read_b128 v[144:147], v195 offset:6400
	ds_read_b128 v[156:159], v195 offset:14592
	ds_read_b128 v[180:183], v195 offset:22784
	ds_read_b128 v[88:91], v195 offset:39168
	ds_read_b64 v[8:9], v196 offset:12800
	ds_read_b32 v10, v36 offset:12800
	s_waitcnt lgkmcnt(7)
	v_pk_mul_f32 v[46:47], v[24:25], v[140:141] op_sel_hi:[0,1]
	v_pk_mul_f32 v[34:35], v[20:21], v[140:141] op_sel_hi:[0,1]
	v_pk_fma_f32 v[46:47], v[24:25], v[142:143], v[46:47] op_sel:[1,0,0] op_sel_hi:[1,1,1]
	v_pk_fma_f32 v[34:35], v[20:21], v[142:143], v[34:35] op_sel:[1,0,0] op_sel_hi:[1,1,1]
	v_pk_fma_f32 v[46:47], v[26:27], v[152:153], v[46:47] op_sel_hi:[0,1,1]
	v_pk_fma_f32 v[34:35], v[22:23], v[152:153], v[34:35] op_sel_hi:[0,1,1]
	v_pk_fma_f32 v[46:47], v[26:27], v[154:155], v[46:47] op_sel:[1,0,0] op_sel_hi:[1,1,1]
	v_pk_fma_f32 v[34:35], v[22:23], v[154:155], v[34:35] op_sel:[1,0,0] op_sel_hi:[1,1,1]
	v_pk_fma_f32 v[20:21], v[176:177], v[4:5], v[20:21] op_sel_hi:[1,0,1]
	v_add_f32_dpp v28, v46, v34 row_half_mirror row_mask:0xf bank_mask:0xf
	v_add_f32_dpp v32, v47, v35 row_half_mirror row_mask:0xf bank_mask:0xf
	v_pk_fma_f32 v[22:23], v[178:179], v[4:5], v[22:23] op_sel_hi:[1,0,1]
	v_add_f32_dpp v28, v28, v28 row_ror:8 row_mask:0xf bank_mask:0xf
	v_add_f32_dpp v32, v32, v32 row_ror:8 row_mask:0xf bank_mask:0xf
	v_pk_fma_f32 v[24:25], v[176:177], v[6:7], v[24:25] op_sel_hi:[1,0,1]
	v_add_f32_dpp v28, v28, v28 quad_perm:[1,0,3,2] row_mask:0xf bank_mask:0xf
	v_add_f32_dpp v32, v32, v32 quad_perm:[1,0,3,2] row_mask:0xf bank_mask:0xf
	v_pk_fma_f32 v[26:27], v[178:179], v[6:7], v[26:27] op_sel_hi:[1,0,1]
	v_add_f32_dpp v28, v28, v28 quad_perm:[2,3,0,1] row_mask:0xf bank_mask:0xf
	v_add_f32_dpp v32, v32, v32 quad_perm:[2,3,0,1] row_mask:0xf bank_mask:0xf
	v_add_f32_e32 v39, v32, v5
	v_mov_b32_dpp v30, v28 row_half_mirror row_mask:0xf bank_mask:0xf
	v_pk_fma_f32 v[20:21], v[84:85], v[28:29], v[20:21] op_sel_hi:[1,0,1] neg_lo:[0,1,0] neg_hi:[0,1,0]
	v_pk_fma_f32 v[22:23], v[86:87], v[28:29], v[22:23] op_sel_hi:[1,0,1] neg_lo:[0,1,0] neg_hi:[0,1,0]
	v_pk_fma_f32 v[24:25], v[84:85], v[30:31], v[24:25] op_sel_hi:[1,0,1] neg_lo:[0,1,0] neg_hi:[0,1,0]
	v_pk_fma_f32 v[26:27], v[86:87], v[30:31], v[26:27] op_sel_hi:[1,0,1] neg_lo:[0,1,0] neg_hi:[0,1,0]
	ds_write_b32 v102, v39 offset:3072
	ds_read_b128 v[140:143], v195 offset:6656
	ds_read_b128 v[152:155], v195 offset:14848
	ds_read_b128 v[176:179], v195 offset:23040
	ds_read_b128 v[84:87], v195 offset:39424
	ds_read_b64 v[4:5], v196 offset:13312
	ds_read_b32 v6, v36 offset:13312
	s_waitcnt lgkmcnt(7)
	v_pk_mul_f32 v[46:47], v[24:25], v[144:145] op_sel_hi:[0,1]
	v_pk_mul_f32 v[34:35], v[20:21], v[144:145] op_sel_hi:[0,1]
	v_pk_fma_f32 v[46:47], v[24:25], v[146:147], v[46:47] op_sel:[1,0,0] op_sel_hi:[1,1,1]
	v_pk_fma_f32 v[34:35], v[20:21], v[146:147], v[34:35] op_sel:[1,0,0] op_sel_hi:[1,1,1]
	v_pk_fma_f32 v[46:47], v[26:27], v[156:157], v[46:47] op_sel_hi:[0,1,1]
	v_pk_fma_f32 v[34:35], v[22:23], v[156:157], v[34:35] op_sel_hi:[0,1,1]
	v_pk_fma_f32 v[46:47], v[26:27], v[158:159], v[46:47] op_sel:[1,0,0] op_sel_hi:[1,1,1]
	v_pk_fma_f32 v[34:35], v[22:23], v[158:159], v[34:35] op_sel:[1,0,0] op_sel_hi:[1,1,1]
	v_pk_fma_f32 v[20:21], v[180:181], v[8:9], v[20:21] op_sel_hi:[1,0,1]
	v_add_f32_dpp v28, v46, v34 row_half_mirror row_mask:0xf bank_mask:0xf
	v_add_f32_dpp v32, v47, v35 row_half_mirror row_mask:0xf bank_mask:0xf
	v_pk_fma_f32 v[22:23], v[182:183], v[8:9], v[22:23] op_sel_hi:[1,0,1]
	v_add_f32_dpp v28, v28, v28 row_ror:8 row_mask:0xf bank_mask:0xf
	v_add_f32_dpp v32, v32, v32 row_ror:8 row_mask:0xf bank_mask:0xf
	v_pk_fma_f32 v[24:25], v[180:181], v[10:11], v[24:25] op_sel_hi:[1,0,1]
	v_add_f32_dpp v28, v28, v28 quad_perm:[1,0,3,2] row_mask:0xf bank_mask:0xf
	v_add_f32_dpp v32, v32, v32 quad_perm:[1,0,3,2] row_mask:0xf bank_mask:0xf
	v_pk_fma_f32 v[26:27], v[182:183], v[10:11], v[26:27] op_sel_hi:[1,0,1]
	v_add_f32_dpp v28, v28, v28 quad_perm:[2,3,0,1] row_mask:0xf bank_mask:0xf
	v_add_f32_dpp v32, v32, v32 quad_perm:[2,3,0,1] row_mask:0xf bank_mask:0xf
	v_add_f32_e32 v39, v32, v9
	v_mov_b32_dpp v30, v28 row_half_mirror row_mask:0xf bank_mask:0xf
	v_pk_fma_f32 v[20:21], v[88:89], v[28:29], v[20:21] op_sel_hi:[1,0,1] neg_lo:[0,1,0] neg_hi:[0,1,0]
	v_pk_fma_f32 v[22:23], v[90:91], v[28:29], v[22:23] op_sel_hi:[1,0,1] neg_lo:[0,1,0] neg_hi:[0,1,0]
	v_pk_fma_f32 v[24:25], v[88:89], v[30:31], v[24:25] op_sel_hi:[1,0,1] neg_lo:[0,1,0] neg_hi:[0,1,0]
	v_pk_fma_f32 v[26:27], v[90:91], v[30:31], v[26:27] op_sel_hi:[1,0,1] neg_lo:[0,1,0] neg_hi:[0,1,0]
	ds_write_b32 v102, v39 offset:3200
	ds_read_b128 v[144:147], v195 offset:6912
	ds_read_b128 v[156:159], v195 offset:15104
	ds_read_b128 v[168:171], v195 offset:31488
	ds_read_b128 v[180:183], v195 offset:23296
	ds_read_b128 v[88:91], v195 offset:39680
	ds_read_b64 v[8:9], v196 offset:13824
	ds_read_b32 v10, v36 offset:13824
	s_waitcnt lgkmcnt(8)
	v_pk_mul_f32 v[46:47], v[24:25], v[140:141] op_sel_hi:[0,1]
	v_pk_mul_f32 v[34:35], v[20:21], v[140:141] op_sel_hi:[0,1]
	v_pk_fma_f32 v[46:47], v[24:25], v[142:143], v[46:47] op_sel:[1,0,0] op_sel_hi:[1,1,1]
	v_pk_fma_f32 v[34:35], v[20:21], v[142:143], v[34:35] op_sel:[1,0,0] op_sel_hi:[1,1,1]
	v_pk_fma_f32 v[46:47], v[26:27], v[152:153], v[46:47] op_sel_hi:[0,1,1]
	v_pk_fma_f32 v[34:35], v[22:23], v[152:153], v[34:35] op_sel_hi:[0,1,1]
	v_pk_fma_f32 v[46:47], v[26:27], v[154:155], v[46:47] op_sel:[1,0,0] op_sel_hi:[1,1,1]
	v_pk_fma_f32 v[34:35], v[22:23], v[154:155], v[34:35] op_sel:[1,0,0] op_sel_hi:[1,1,1]
	v_pk_fma_f32 v[20:21], v[176:177], v[4:5], v[20:21] op_sel_hi:[1,0,1]
	v_add_f32_dpp v28, v46, v34 row_half_mirror row_mask:0xf bank_mask:0xf
	v_add_f32_dpp v32, v47, v35 row_half_mirror row_mask:0xf bank_mask:0xf
	v_pk_fma_f32 v[22:23], v[178:179], v[4:5], v[22:23] op_sel_hi:[1,0,1]
	v_add_f32_dpp v28, v28, v28 row_ror:8 row_mask:0xf bank_mask:0xf
	v_add_f32_dpp v32, v32, v32 row_ror:8 row_mask:0xf bank_mask:0xf
	v_pk_fma_f32 v[24:25], v[176:177], v[6:7], v[24:25] op_sel_hi:[1,0,1]
	v_add_f32_dpp v28, v28, v28 quad_perm:[1,0,3,2] row_mask:0xf bank_mask:0xf
	v_add_f32_dpp v32, v32, v32 quad_perm:[1,0,3,2] row_mask:0xf bank_mask:0xf
	v_pk_fma_f32 v[26:27], v[178:179], v[6:7], v[26:27] op_sel_hi:[1,0,1]
	v_add_f32_dpp v28, v28, v28 quad_perm:[2,3,0,1] row_mask:0xf bank_mask:0xf
	v_add_f32_dpp v32, v32, v32 quad_perm:[2,3,0,1] row_mask:0xf bank_mask:0xf
	v_add_f32_e32 v39, v32, v5
	v_mov_b32_dpp v30, v28 row_half_mirror row_mask:0xf bank_mask:0xf
	v_pk_fma_f32 v[20:21], v[84:85], v[28:29], v[20:21] op_sel_hi:[1,0,1] neg_lo:[0,1,0] neg_hi:[0,1,0]
	v_pk_fma_f32 v[22:23], v[86:87], v[28:29], v[22:23] op_sel_hi:[1,0,1] neg_lo:[0,1,0] neg_hi:[0,1,0]
	v_pk_fma_f32 v[24:25], v[84:85], v[30:31], v[24:25] op_sel_hi:[1,0,1] neg_lo:[0,1,0] neg_hi:[0,1,0]
	v_pk_fma_f32 v[26:27], v[86:87], v[30:31], v[26:27] op_sel_hi:[1,0,1] neg_lo:[0,1,0] neg_hi:[0,1,0]
	ds_write_b32 v102, v39 offset:3328
	ds_read_b128 v[140:143], v195 offset:7168
	ds_read_b128 v[152:155], v195 offset:15360
	ds_read_b128 v[176:179], v195 offset:23552
	ds_read_b128 v[84:87], v195 offset:39936
	ds_read_b64 v[4:5], v196 offset:14336
	ds_read_b32 v6, v36 offset:14336
	s_waitcnt lgkmcnt(7)
	v_pk_mul_f32 v[46:47], v[24:25], v[144:145] op_sel_hi:[0,1]
	v_pk_mul_f32 v[34:35], v[20:21], v[144:145] op_sel_hi:[0,1]
	v_pk_fma_f32 v[46:47], v[24:25], v[146:147], v[46:47] op_sel:[1,0,0] op_sel_hi:[1,1,1]
	v_pk_fma_f32 v[34:35], v[20:21], v[146:147], v[34:35] op_sel:[1,0,0] op_sel_hi:[1,1,1]
	v_pk_fma_f32 v[46:47], v[26:27], v[156:157], v[46:47] op_sel_hi:[0,1,1]
	v_pk_fma_f32 v[34:35], v[22:23], v[156:157], v[34:35] op_sel_hi:[0,1,1]
	v_pk_fma_f32 v[46:47], v[26:27], v[158:159], v[46:47] op_sel:[1,0,0] op_sel_hi:[1,1,1]
	v_pk_fma_f32 v[34:35], v[22:23], v[158:159], v[34:35] op_sel:[1,0,0] op_sel_hi:[1,1,1]
	v_pk_mul_f32 v[20:21], v[20:21], v[168:169]
	v_add_f32_dpp v28, v46, v34 row_half_mirror row_mask:0xf bank_mask:0xf
	v_add_f32_dpp v32, v47, v35 row_half_mirror row_mask:0xf bank_mask:0xf
	v_pk_mul_f32 v[22:23], v[22:23], v[170:171]
	v_add_f32_dpp v28, v28, v28 row_ror:8 row_mask:0xf bank_mask:0xf
	v_add_f32_dpp v32, v32, v32 row_ror:8 row_mask:0xf bank_mask:0xf
	v_pk_mul_f32 v[24:25], v[24:25], v[168:169]
	v_add_f32_dpp v28, v28, v28 quad_perm:[1,0,3,2] row_mask:0xf bank_mask:0xf
	v_add_f32_dpp v32, v32, v32 quad_perm:[1,0,3,2] row_mask:0xf bank_mask:0xf
	v_pk_mul_f32 v[26:27], v[26:27], v[170:171]
	v_add_f32_dpp v28, v28, v28 quad_perm:[2,3,0,1] row_mask:0xf bank_mask:0xf
	v_add_f32_dpp v32, v32, v32 quad_perm:[2,3,0,1] row_mask:0xf bank_mask:0xf
	v_pk_fma_f32 v[20:21], v[180:181], v[8:9], v[20:21] op_sel_hi:[1,0,1]
	v_mov_b32_dpp v30, v28 row_half_mirror row_mask:0xf bank_mask:0xf
	v_pk_fma_f32 v[22:23], v[182:183], v[8:9], v[22:23] op_sel_hi:[1,0,1]
	v_pk_fma_f32 v[24:25], v[180:181], v[10:11], v[24:25] op_sel_hi:[1,0,1]
	v_pk_fma_f32 v[26:27], v[182:183], v[10:11], v[26:27] op_sel_hi:[1,0,1]
	v_pk_fma_f32 v[20:21], v[88:89], v[28:29], v[20:21] op_sel_hi:[1,0,1] neg_lo:[0,1,0] neg_hi:[0,1,0]
	v_pk_fma_f32 v[22:23], v[90:91], v[28:29], v[22:23] op_sel_hi:[1,0,1] neg_lo:[0,1,0] neg_hi:[0,1,0]
	v_pk_fma_f32 v[24:25], v[88:89], v[30:31], v[24:25] op_sel_hi:[1,0,1] neg_lo:[0,1,0] neg_hi:[0,1,0]
	v_pk_fma_f32 v[26:27], v[90:91], v[30:31], v[26:27] op_sel_hi:[1,0,1] neg_lo:[0,1,0] neg_hi:[0,1,0]
	v_add_f32_e32 v39, v32, v9
	ds_write_b32 v102, v39 offset:3456
	ds_read_b128 v[144:147], v195 offset:7424
	ds_read_b128 v[156:159], v195 offset:15616
	ds_read_b128 v[180:183], v195 offset:23808
	ds_read_b128 v[88:91], v195 offset:40192
	ds_read_b64 v[8:9], v196 offset:14848
	ds_read_b32 v10, v36 offset:14848
	s_waitcnt lgkmcnt(7)
	v_pk_mul_f32 v[46:47], v[24:25], v[140:141] op_sel_hi:[0,1]
	v_pk_mul_f32 v[34:35], v[20:21], v[140:141] op_sel_hi:[0,1]
	v_pk_fma_f32 v[46:47], v[24:25], v[142:143], v[46:47] op_sel:[1,0,0] op_sel_hi:[1,1,1]
	v_pk_fma_f32 v[34:35], v[20:21], v[142:143], v[34:35] op_sel:[1,0,0] op_sel_hi:[1,1,1]
	v_pk_fma_f32 v[46:47], v[26:27], v[152:153], v[46:47] op_sel_hi:[0,1,1]
	v_pk_fma_f32 v[34:35], v[22:23], v[152:153], v[34:35] op_sel_hi:[0,1,1]
	v_pk_fma_f32 v[46:47], v[26:27], v[154:155], v[46:47] op_sel:[1,0,0] op_sel_hi:[1,1,1]
	v_pk_fma_f32 v[34:35], v[22:23], v[154:155], v[34:35] op_sel:[1,0,0] op_sel_hi:[1,1,1]
	v_pk_fma_f32 v[20:21], v[176:177], v[4:5], v[20:21] op_sel_hi:[1,0,1]
	v_add_f32_dpp v28, v46, v34 row_half_mirror row_mask:0xf bank_mask:0xf
	v_add_f32_dpp v32, v47, v35 row_half_mirror row_mask:0xf bank_mask:0xf
	v_pk_fma_f32 v[22:23], v[178:179], v[4:5], v[22:23] op_sel_hi:[1,0,1]
	v_add_f32_dpp v28, v28, v28 row_ror:8 row_mask:0xf bank_mask:0xf
	v_add_f32_dpp v32, v32, v32 row_ror:8 row_mask:0xf bank_mask:0xf
	v_pk_fma_f32 v[24:25], v[176:177], v[6:7], v[24:25] op_sel_hi:[1,0,1]
	v_add_f32_dpp v28, v28, v28 quad_perm:[1,0,3,2] row_mask:0xf bank_mask:0xf
	v_add_f32_dpp v32, v32, v32 quad_perm:[1,0,3,2] row_mask:0xf bank_mask:0xf
	v_pk_fma_f32 v[26:27], v[178:179], v[6:7], v[26:27] op_sel_hi:[1,0,1]
	v_add_f32_dpp v28, v28, v28 quad_perm:[2,3,0,1] row_mask:0xf bank_mask:0xf
	v_add_f32_dpp v32, v32, v32 quad_perm:[2,3,0,1] row_mask:0xf bank_mask:0xf
	v_add_f32_e32 v39, v32, v5
	v_mov_b32_dpp v30, v28 row_half_mirror row_mask:0xf bank_mask:0xf
	v_pk_fma_f32 v[20:21], v[84:85], v[28:29], v[20:21] op_sel_hi:[1,0,1] neg_lo:[0,1,0] neg_hi:[0,1,0]
	v_pk_fma_f32 v[22:23], v[86:87], v[28:29], v[22:23] op_sel_hi:[1,0,1] neg_lo:[0,1,0] neg_hi:[0,1,0]
	v_pk_fma_f32 v[24:25], v[84:85], v[30:31], v[24:25] op_sel_hi:[1,0,1] neg_lo:[0,1,0] neg_hi:[0,1,0]
	v_pk_fma_f32 v[26:27], v[86:87], v[30:31], v[26:27] op_sel_hi:[1,0,1] neg_lo:[0,1,0] neg_hi:[0,1,0]
	ds_write_b32 v102, v39 offset:3584
	ds_read_b128 v[140:143], v195 offset:7680
	ds_read_b128 v[152:155], v195 offset:15872
	ds_read_b128 v[176:179], v195 offset:24064
	ds_read_b128 v[84:87], v195 offset:40448
	ds_read_b64 v[4:5], v196 offset:15360
	ds_read_b32 v6, v36 offset:15360
	s_waitcnt lgkmcnt(7)
	v_pk_mul_f32 v[46:47], v[24:25], v[144:145] op_sel_hi:[0,1]
	v_pk_mul_f32 v[34:35], v[20:21], v[144:145] op_sel_hi:[0,1]
	v_pk_fma_f32 v[46:47], v[24:25], v[146:147], v[46:47] op_sel:[1,0,0] op_sel_hi:[1,1,1]
	v_pk_fma_f32 v[34:35], v[20:21], v[146:147], v[34:35] op_sel:[1,0,0] op_sel_hi:[1,1,1]
	v_pk_fma_f32 v[46:47], v[26:27], v[156:157], v[46:47] op_sel_hi:[0,1,1]
	v_pk_fma_f32 v[34:35], v[22:23], v[156:157], v[34:35] op_sel_hi:[0,1,1]
	v_pk_fma_f32 v[46:47], v[26:27], v[158:159], v[46:47] op_sel:[1,0,0] op_sel_hi:[1,1,1]
	v_pk_fma_f32 v[34:35], v[22:23], v[158:159], v[34:35] op_sel:[1,0,0] op_sel_hi:[1,1,1]
	v_pk_fma_f32 v[20:21], v[180:181], v[8:9], v[20:21] op_sel_hi:[1,0,1]
	v_add_f32_dpp v28, v46, v34 row_half_mirror row_mask:0xf bank_mask:0xf
	v_add_f32_dpp v32, v47, v35 row_half_mirror row_mask:0xf bank_mask:0xf
	v_pk_fma_f32 v[22:23], v[182:183], v[8:9], v[22:23] op_sel_hi:[1,0,1]
	v_add_f32_dpp v28, v28, v28 row_ror:8 row_mask:0xf bank_mask:0xf
	v_add_f32_dpp v32, v32, v32 row_ror:8 row_mask:0xf bank_mask:0xf
	v_pk_fma_f32 v[24:25], v[180:181], v[10:11], v[24:25] op_sel_hi:[1,0,1]
	v_add_f32_dpp v28, v28, v28 quad_perm:[1,0,3,2] row_mask:0xf bank_mask:0xf
	v_add_f32_dpp v32, v32, v32 quad_perm:[1,0,3,2] row_mask:0xf bank_mask:0xf
	v_pk_fma_f32 v[26:27], v[182:183], v[10:11], v[26:27] op_sel_hi:[1,0,1]
	v_add_f32_dpp v28, v28, v28 quad_perm:[2,3,0,1] row_mask:0xf bank_mask:0xf
	v_add_f32_dpp v32, v32, v32 quad_perm:[2,3,0,1] row_mask:0xf bank_mask:0xf
	v_add_f32_e32 v39, v32, v9
	v_mov_b32_dpp v30, v28 row_half_mirror row_mask:0xf bank_mask:0xf
	v_pk_fma_f32 v[20:21], v[88:89], v[28:29], v[20:21] op_sel_hi:[1,0,1] neg_lo:[0,1,0] neg_hi:[0,1,0]
	v_pk_fma_f32 v[22:23], v[90:91], v[28:29], v[22:23] op_sel_hi:[1,0,1] neg_lo:[0,1,0] neg_hi:[0,1,0]
	v_pk_fma_f32 v[24:25], v[88:89], v[30:31], v[24:25] op_sel_hi:[1,0,1] neg_lo:[0,1,0] neg_hi:[0,1,0]
	v_pk_fma_f32 v[26:27], v[90:91], v[30:31], v[26:27] op_sel_hi:[1,0,1] neg_lo:[0,1,0] neg_hi:[0,1,0]
	ds_write_b32 v102, v39 offset:3712
	ds_read_b128 v[144:147], v195 offset:7936
	ds_read_b128 v[156:159], v195 offset:16128
	ds_read_b128 v[168:171], v195 offset:32512
	ds_read_b128 v[180:183], v195 offset:24320
	ds_read_b128 v[88:91], v195 offset:40704
	ds_read_b64 v[8:9], v196 offset:15872
	ds_read_b32 v10, v36 offset:15872
	s_waitcnt lgkmcnt(8)
	v_pk_mul_f32 v[46:47], v[24:25], v[140:141] op_sel_hi:[0,1]
	v_pk_mul_f32 v[34:35], v[20:21], v[140:141] op_sel_hi:[0,1]
	v_pk_fma_f32 v[46:47], v[24:25], v[142:143], v[46:47] op_sel:[1,0,0] op_sel_hi:[1,1,1]
	v_pk_fma_f32 v[34:35], v[20:21], v[142:143], v[34:35] op_sel:[1,0,0] op_sel_hi:[1,1,1]
	v_pk_fma_f32 v[46:47], v[26:27], v[152:153], v[46:47] op_sel_hi:[0,1,1]
	v_pk_fma_f32 v[34:35], v[22:23], v[152:153], v[34:35] op_sel_hi:[0,1,1]
	v_pk_fma_f32 v[46:47], v[26:27], v[154:155], v[46:47] op_sel:[1,0,0] op_sel_hi:[1,1,1]
	v_pk_fma_f32 v[34:35], v[22:23], v[154:155], v[34:35] op_sel:[1,0,0] op_sel_hi:[1,1,1]
	v_pk_fma_f32 v[20:21], v[176:177], v[4:5], v[20:21] op_sel_hi:[1,0,1]
	v_add_f32_dpp v28, v46, v34 row_half_mirror row_mask:0xf bank_mask:0xf
	v_add_f32_dpp v32, v47, v35 row_half_mirror row_mask:0xf bank_mask:0xf
	v_pk_fma_f32 v[22:23], v[178:179], v[4:5], v[22:23] op_sel_hi:[1,0,1]
	v_add_f32_dpp v28, v28, v28 row_ror:8 row_mask:0xf bank_mask:0xf
	v_add_f32_dpp v32, v32, v32 row_ror:8 row_mask:0xf bank_mask:0xf
	v_pk_fma_f32 v[24:25], v[176:177], v[6:7], v[24:25] op_sel_hi:[1,0,1]
	v_add_f32_dpp v28, v28, v28 quad_perm:[1,0,3,2] row_mask:0xf bank_mask:0xf
	v_add_f32_dpp v32, v32, v32 quad_perm:[1,0,3,2] row_mask:0xf bank_mask:0xf
	v_pk_fma_f32 v[26:27], v[178:179], v[6:7], v[26:27] op_sel_hi:[1,0,1]
	v_add_f32_dpp v28, v28, v28 quad_perm:[2,3,0,1] row_mask:0xf bank_mask:0xf
	v_add_f32_dpp v32, v32, v32 quad_perm:[2,3,0,1] row_mask:0xf bank_mask:0xf
	v_add_f32_e32 v39, v32, v5
	v_mov_b32_dpp v30, v28 row_half_mirror row_mask:0xf bank_mask:0xf
	v_pk_fma_f32 v[20:21], v[84:85], v[28:29], v[20:21] op_sel_hi:[1,0,1] neg_lo:[0,1,0] neg_hi:[0,1,0]
	v_pk_fma_f32 v[22:23], v[86:87], v[28:29], v[22:23] op_sel_hi:[1,0,1] neg_lo:[0,1,0] neg_hi:[0,1,0]
	v_pk_fma_f32 v[24:25], v[84:85], v[30:31], v[24:25] op_sel_hi:[1,0,1] neg_lo:[0,1,0] neg_hi:[0,1,0]
	v_pk_fma_f32 v[26:27], v[86:87], v[30:31], v[26:27] op_sel_hi:[1,0,1] neg_lo:[0,1,0] neg_hi:[0,1,0]
	ds_write_b32 v102, v39 offset:3840
	s_waitcnt lgkmcnt(1)
	v_pk_mul_f32 v[46:47], v[24:25], v[144:145] op_sel_hi:[0,1]
	v_pk_mul_f32 v[34:35], v[20:21], v[144:145] op_sel_hi:[0,1]
	v_pk_fma_f32 v[46:47], v[24:25], v[146:147], v[46:47] op_sel:[1,0,0] op_sel_hi:[1,1,1]
	v_pk_fma_f32 v[34:35], v[20:21], v[146:147], v[34:35] op_sel:[1,0,0] op_sel_hi:[1,1,1]
	v_pk_fma_f32 v[46:47], v[26:27], v[156:157], v[46:47] op_sel_hi:[0,1,1]
	v_pk_fma_f32 v[34:35], v[22:23], v[156:157], v[34:35] op_sel_hi:[0,1,1]
	v_pk_fma_f32 v[46:47], v[26:27], v[158:159], v[46:47] op_sel:[1,0,0] op_sel_hi:[1,1,1]
	v_pk_fma_f32 v[34:35], v[22:23], v[158:159], v[34:35] op_sel:[1,0,0] op_sel_hi:[1,1,1]
	v_pk_mul_f32 v[20:21], v[20:21], v[168:169]
	v_add_f32_dpp v28, v46, v34 row_half_mirror row_mask:0xf bank_mask:0xf
	v_add_f32_dpp v32, v47, v35 row_half_mirror row_mask:0xf bank_mask:0xf
	v_pk_mul_f32 v[22:23], v[22:23], v[170:171]
	v_add_f32_dpp v28, v28, v28 row_ror:8 row_mask:0xf bank_mask:0xf
	v_add_f32_dpp v32, v32, v32 row_ror:8 row_mask:0xf bank_mask:0xf
	v_pk_mul_f32 v[24:25], v[24:25], v[168:169]
	v_add_f32_dpp v28, v28, v28 quad_perm:[1,0,3,2] row_mask:0xf bank_mask:0xf
	v_add_f32_dpp v32, v32, v32 quad_perm:[1,0,3,2] row_mask:0xf bank_mask:0xf
	v_pk_mul_f32 v[26:27], v[26:27], v[170:171]
	v_add_f32_dpp v28, v28, v28 quad_perm:[2,3,0,1] row_mask:0xf bank_mask:0xf
	v_add_f32_dpp v32, v32, v32 quad_perm:[2,3,0,1] row_mask:0xf bank_mask:0xf
	v_pk_fma_f32 v[20:21], v[180:181], v[8:9], v[20:21] op_sel_hi:[1,0,1]
	v_mov_b32_dpp v30, v28 row_half_mirror row_mask:0xf bank_mask:0xf
	v_pk_fma_f32 v[22:23], v[182:183], v[8:9], v[22:23] op_sel_hi:[1,0,1]
	v_pk_fma_f32 v[24:25], v[180:181], v[10:11], v[24:25] op_sel_hi:[1,0,1]
	v_pk_fma_f32 v[26:27], v[182:183], v[10:11], v[26:27] op_sel_hi:[1,0,1]
	v_pk_fma_f32 v[20:21], v[88:89], v[28:29], v[20:21] op_sel_hi:[1,0,1] neg_lo:[0,1,0] neg_hi:[0,1,0]
	v_pk_fma_f32 v[22:23], v[90:91], v[28:29], v[22:23] op_sel_hi:[1,0,1] neg_lo:[0,1,0] neg_hi:[0,1,0]
	v_pk_fma_f32 v[24:25], v[88:89], v[30:31], v[24:25] op_sel_hi:[1,0,1] neg_lo:[0,1,0] neg_hi:[0,1,0]
	v_pk_fma_f32 v[26:27], v[90:91], v[30:31], v[26:27] op_sel_hi:[1,0,1] neg_lo:[0,1,0] neg_hi:[0,1,0]
	v_add_f32_e32 v39, v32, v9
	ds_write_b32 v102, v39 offset:3968
	s_waitcnt lgkmcnt(0)
	s_barrier
	s_add_i32 s8, s8, 1
	s_cmp_eq_u32 s8, 64
	s_cbranch_scc0 .Lrw_scan_loop
	s_setprio 0
	s_branch .LBB0_183
